# v046 + hyconv: L2 prefetch of the post-ladder u/gate rows issued at the head of each Toeplitz ladder
# baseline (speedup 1.0000x reference)
.LBB0_800:
	s_or_b64 exec, exec, s[0:1]
	ds_read_b128 v[6:9], v97 offset:4064
	ds_read_b128 v[10:13], v97 offset:4000
	ds_read_b128 v[38:41], v149
	ds_read_b128 v[34:37], v97 offset:3680
	ds_read_b128 v[66:69], v97 offset:3616
	ds_read_b128 v[18:21], v97 offset:3936
	ds_read_b128 v[22:25], v97 offset:3872
	ds_read_b128 v[26:29], v97 offset:3808
	ds_read_b128 v[30:33], v97 offset:3744
	ds_read_b128 v[14:17], v97 offset:4128
	ds_read_b128 v[70:73], v150
	s_waitcnt lgkmcnt(7)
	v_mfma_f32_16x16x32_bf16 v[74:77], v[34:37], v[38:41], 0
	s_add_i32 s0, s24, 0x800
	s_mul_hi_i32 s1, s0, 0xc000
	s_mul_i32 s0, s0, 0xc000
	v_mfma_f32_16x16x32_bf16 v[42:45], v[6:9], v[38:41], 0
	s_add_u32 s2, s20, s0
	s_addc_u32 s3, s68, s1
	v_lshlrev_b32_e32 v222, 1, v96
	v_mov_b32_e32 v223, 0
	v_lshl_add_u64 v[222:223], s[2:3], 0, v[222:223]
	v_lshl_add_u64 v[222:223], v[98:99], 1, v[222:223]
	v_lshl_add_u64 v[222:223], v[222:223], 0, s[16:17]
	global_load_dword v224, v[222:223], off
	global_load_dword v224, v[222:223], off offset:64
	global_load_dword v224, v[222:223], off offset:128
	global_load_dword v224, v[222:223], off offset:192
	global_load_dword v224, v[222:223], off offset:256
	global_load_dword v224, v[222:223], off offset:320
	global_load_dword v224, v[222:223], off offset:384
	global_load_dword v224, v[222:223], off offset:448
	v_mov_b32_e32 v137, 0
	v_mfma_f32_16x16x32_bf16 v[46:49], v[10:13], v[38:41], 0
	s_waitcnt lgkmcnt(5)
	v_mfma_f32_16x16x32_bf16 v[50:53], v[18:21], v[38:41], 0
	s_waitcnt lgkmcnt(4)
	v_mfma_f32_16x16x32_bf16 v[54:57], v[22:25], v[38:41], 0
	s_waitcnt lgkmcnt(3)
	v_mfma_f32_16x16x32_bf16 v[58:61], v[26:29], v[38:41], 0
	s_waitcnt lgkmcnt(2)
	v_mfma_f32_16x16x32_bf16 v[62:65], v[30:33], v[38:41], 0
	v_mfma_f32_16x16x32_bf16 v[38:41], v[66:69], v[38:41], 0
	s_waitcnt lgkmcnt(0)
	v_mfma_f32_16x16x32_bf16 v[66:69], v[30:33], v[70:73], v[74:77]
	s_nop 2
	ds_read_b128 v[74:77], v97 offset:4192
	v_mfma_f32_16x16x32_bf16 v[34:37], v[34:37], v[70:73], v[38:41]
	s_nop 2
	ds_read_b128 v[38:41], v150 offset:64
	v_mfma_f32_16x16x32_bf16 v[42:45], v[14:17], v[70:73], v[42:45]
	v_mfma_f32_16x16x32_bf16 v[46:49], v[6:9], v[70:73], v[46:49]
	v_mfma_f32_16x16x32_bf16 v[50:53], v[10:13], v[70:73], v[50:53]
	v_mfma_f32_16x16x32_bf16 v[54:57], v[18:21], v[70:73], v[54:57]
	v_mfma_f32_16x16x32_bf16 v[58:61], v[22:25], v[70:73], v[58:61]
	v_mfma_f32_16x16x32_bf16 v[62:65], v[26:29], v[70:73], v[62:65]
	ds_read_b128 v[70:73], v97 offset:4256
	s_waitcnt lgkmcnt(1)
	v_mfma_f32_16x16x32_bf16 v[30:33], v[30:33], v[38:41], v[34:37]
	s_nop 2
	ds_read_b128 v[34:37], v150 offset:128
	v_mfma_f32_16x16x32_bf16 v[42:45], v[74:77], v[38:41], v[42:45]
	v_mfma_f32_16x16x32_bf16 v[46:49], v[14:17], v[38:41], v[46:49]
	v_mfma_f32_16x16x32_bf16 v[50:53], v[6:9], v[38:41], v[50:53]
	v_mfma_f32_16x16x32_bf16 v[54:57], v[10:13], v[38:41], v[54:57]
	v_mfma_f32_16x16x32_bf16 v[58:61], v[18:21], v[38:41], v[58:61]
	v_mfma_f32_16x16x32_bf16 v[62:65], v[22:25], v[38:41], v[62:65]
	v_mfma_f32_16x16x32_bf16 v[66:69], v[26:29], v[38:41], v[66:69]
	s_waitcnt lgkmcnt(0)
	v_mfma_f32_16x16x32_bf16 v[38:41], v[70:73], v[34:37], v[42:45]
	v_mfma_f32_16x16x32_bf16 v[42:45], v[74:77], v[34:37], v[46:49]
	v_mfma_f32_16x16x32_bf16 v[46:49], v[14:17], v[34:37], v[50:53]
	v_mfma_f32_16x16x32_bf16 v[50:53], v[6:9], v[34:37], v[54:57]
	v_mfma_f32_16x16x32_bf16 v[54:57], v[10:13], v[34:37], v[58:61]
	v_mfma_f32_16x16x32_bf16 v[58:61], v[18:21], v[34:37], v[62:65]
	v_mfma_f32_16x16x32_bf16 v[62:65], v[22:25], v[34:37], v[66:69]
	s_nop 2
	ds_read_b128 v[66:69], v97 offset:4320
	v_mfma_f32_16x16x32_bf16 v[26:29], v[26:29], v[34:37], v[30:33]
	s_nop 2
	ds_read_b128 v[30:33], v150 offset:192
	s_waitcnt lgkmcnt(0)
	v_mfma_f32_16x16x32_bf16 v[34:37], v[66:69], v[30:33], v[38:41]
	v_mfma_f32_16x16x32_bf16 v[38:41], v[70:73], v[30:33], v[42:45]
	v_mfma_f32_16x16x32_bf16 v[42:45], v[74:77], v[30:33], v[46:49]
	v_mfma_f32_16x16x32_bf16 v[46:49], v[14:17], v[30:33], v[50:53]
	v_mfma_f32_16x16x32_bf16 v[50:53], v[6:9], v[30:33], v[54:57]
	v_mfma_f32_16x16x32_bf16 v[54:57], v[10:13], v[30:33], v[58:61]
	v_mfma_f32_16x16x32_bf16 v[58:61], v[18:21], v[30:33], v[62:65]
	s_nop 2
	ds_read_b128 v[62:65], v97 offset:4384
	v_mfma_f32_16x16x32_bf16 v[22:25], v[22:25], v[30:33], v[26:29]
	s_nop 2
	ds_read_b128 v[26:29], v150 offset:256
	s_waitcnt lgkmcnt(0)
	v_mfma_f32_16x16x32_bf16 v[30:33], v[62:65], v[26:29], v[34:37]
	v_mfma_f32_16x16x32_bf16 v[34:37], v[66:69], v[26:29], v[38:41]
	v_mfma_f32_16x16x32_bf16 v[38:41], v[70:73], v[26:29], v[42:45]
	v_mfma_f32_16x16x32_bf16 v[42:45], v[74:77], v[26:29], v[46:49]
	v_mfma_f32_16x16x32_bf16 v[46:49], v[14:17], v[26:29], v[50:53]
	v_mfma_f32_16x16x32_bf16 v[50:53], v[6:9], v[26:29], v[54:57]
	v_mfma_f32_16x16x32_bf16 v[54:57], v[10:13], v[26:29], v[58:61]
	s_nop 2
	ds_read_b128 v[58:61], v97 offset:4448
	v_mfma_f32_16x16x32_bf16 v[18:21], v[18:21], v[26:29], v[22:25]
	s_nop 2
	ds_read_b128 v[22:25], v150 offset:320
	s_waitcnt lgkmcnt(0)
	v_mfma_f32_16x16x32_bf16 v[26:29], v[58:61], v[22:25], v[30:33]
	v_mfma_f32_16x16x32_bf16 v[30:33], v[62:65], v[22:25], v[34:37]
	v_mfma_f32_16x16x32_bf16 v[34:37], v[66:69], v[22:25], v[38:41]
	v_mfma_f32_16x16x32_bf16 v[38:41], v[70:73], v[22:25], v[42:45]
	v_mfma_f32_16x16x32_bf16 v[42:45], v[74:77], v[22:25], v[46:49]
	v_mfma_f32_16x16x32_bf16 v[46:49], v[14:17], v[22:25], v[50:53]
	v_mfma_f32_16x16x32_bf16 v[50:53], v[6:9], v[22:25], v[54:57]
	s_nop 2
	ds_read_b128 v[54:57], v97 offset:4512
	v_mfma_f32_16x16x32_bf16 v[10:13], v[10:13], v[22:25], v[18:21]
	s_nop 2
	ds_read_b128 v[18:21], v150 offset:384
	s_waitcnt lgkmcnt(0)
	v_mfma_f32_16x16x32_bf16 v[22:25], v[54:57], v[18:21], v[26:29]
	v_mfma_f32_16x16x32_bf16 v[26:29], v[58:61], v[18:21], v[30:33]
	v_mfma_f32_16x16x32_bf16 v[30:33], v[62:65], v[18:21], v[34:37]
	v_mfma_f32_16x16x32_bf16 v[34:37], v[66:69], v[18:21], v[38:41]
	v_mfma_f32_16x16x32_bf16 v[38:41], v[70:73], v[18:21], v[42:45]
	v_mfma_f32_16x16x32_bf16 v[42:45], v[74:77], v[18:21], v[46:49]
	v_mfma_f32_16x16x32_bf16 v[46:49], v[14:17], v[18:21], v[50:53]
	s_nop 2
	ds_read_b128 v[50:53], v97 offset:4576
	v_mfma_f32_16x16x32_bf16 v[6:9], v[6:9], v[18:21], v[10:13]
	s_nop 2
	ds_read_b128 v[10:13], v150 offset:448
	s_waitcnt lgkmcnt(0)
	v_mfma_f32_16x16x32_bf16 v[18:21], v[50:53], v[10:13], v[22:25]
	v_mfma_f32_16x16x32_bf16 v[22:25], v[54:57], v[10:13], v[26:29]
	v_mfma_f32_16x16x32_bf16 v[26:29], v[58:61], v[10:13], v[30:33]
	v_mfma_f32_16x16x32_bf16 v[30:33], v[62:65], v[10:13], v[34:37]
	v_mfma_f32_16x16x32_bf16 v[34:37], v[66:69], v[10:13], v[38:41]
	v_mfma_f32_16x16x32_bf16 v[38:41], v[70:73], v[10:13], v[42:45]
	v_mfma_f32_16x16x32_bf16 v[42:45], v[74:77], v[10:13], v[46:49]
	s_nop 2
	ds_read_b128 v[46:49], v97 offset:4640
	v_mfma_f32_16x16x32_bf16 v[6:9], v[14:17], v[10:13], v[6:9]
	ds_read_b128 v[10:13], v150 offset:512
	s_waitcnt lgkmcnt(0)
	v_mfma_f32_16x16x32_bf16 v[6:9], v[74:77], v[10:13], v[6:9]
	ds_read_b128 v[74:77], v97 offset:4768
	v_mfma_f32_16x16x32_bf16 v[14:17], v[46:49], v[10:13], v[18:21]
	v_mfma_f32_16x16x32_bf16 v[18:21], v[50:53], v[10:13], v[22:25]
	v_mfma_f32_16x16x32_bf16 v[22:25], v[54:57], v[10:13], v[26:29]
	v_mfma_f32_16x16x32_bf16 v[26:29], v[58:61], v[10:13], v[30:33]
	v_mfma_f32_16x16x32_bf16 v[30:33], v[62:65], v[10:13], v[34:37]
	v_mfma_f32_16x16x32_bf16 v[34:37], v[66:69], v[10:13], v[38:41]
	v_mfma_f32_16x16x32_bf16 v[38:41], v[70:73], v[10:13], v[42:45]
	ds_read_b128 v[10:13], v150 offset:576
	s_nop 1
	ds_read_b128 v[42:45], v97 offset:4704
	s_waitcnt lgkmcnt(1)
	v_mfma_f32_16x16x32_bf16 v[18:21], v[46:49], v[10:13], v[18:21]
	v_mfma_f32_16x16x32_bf16 v[22:25], v[50:53], v[10:13], v[22:25]
	v_mfma_f32_16x16x32_bf16 v[26:29], v[54:57], v[10:13], v[26:29]
	v_mfma_f32_16x16x32_bf16 v[30:33], v[58:61], v[10:13], v[30:33]
	v_mfma_f32_16x16x32_bf16 v[34:37], v[62:65], v[10:13], v[34:37]
	v_mfma_f32_16x16x32_bf16 v[38:41], v[66:69], v[10:13], v[38:41]
	v_mfma_f32_16x16x32_bf16 v[6:9], v[70:73], v[10:13], v[6:9]
	ds_read_b128 v[70:73], v97 offset:4832
	s_waitcnt lgkmcnt(1)
	v_mfma_f32_16x16x32_bf16 v[14:17], v[42:45], v[10:13], v[14:17]
	ds_read_b128 v[10:13], v150 offset:640
	s_waitcnt lgkmcnt(0)
	v_mfma_f32_16x16x32_bf16 v[14:17], v[74:77], v[10:13], v[14:17]
	v_mfma_f32_16x16x32_bf16 v[18:21], v[42:45], v[10:13], v[18:21]
	v_mfma_f32_16x16x32_bf16 v[22:25], v[46:49], v[10:13], v[22:25]
	v_mfma_f32_16x16x32_bf16 v[26:29], v[50:53], v[10:13], v[26:29]
	v_mfma_f32_16x16x32_bf16 v[30:33], v[54:57], v[10:13], v[30:33]
	v_mfma_f32_16x16x32_bf16 v[34:37], v[58:61], v[10:13], v[34:37]
	v_mfma_f32_16x16x32_bf16 v[38:41], v[62:65], v[10:13], v[38:41]
	v_mfma_f32_16x16x32_bf16 v[6:9], v[66:69], v[10:13], v[6:9]
	ds_read_b128 v[10:13], v150 offset:704
	ds_read_b128 v[66:69], v97 offset:4896
	s_waitcnt lgkmcnt(1)
	v_mfma_f32_16x16x32_bf16 v[14:17], v[70:73], v[10:13], v[14:17]
	v_mfma_f32_16x16x32_bf16 v[18:21], v[74:77], v[10:13], v[18:21]
	v_mfma_f32_16x16x32_bf16 v[22:25], v[42:45], v[10:13], v[22:25]
	v_mfma_f32_16x16x32_bf16 v[26:29], v[46:49], v[10:13], v[26:29]
	v_mfma_f32_16x16x32_bf16 v[30:33], v[50:53], v[10:13], v[30:33]
	v_mfma_f32_16x16x32_bf16 v[34:37], v[54:57], v[10:13], v[34:37]
	v_mfma_f32_16x16x32_bf16 v[38:41], v[58:61], v[10:13], v[38:41]
	v_mfma_f32_16x16x32_bf16 v[6:9], v[62:65], v[10:13], v[6:9]
	ds_read_b128 v[10:13], v150 offset:768
	ds_read_b128 v[62:65], v97 offset:4960
	s_waitcnt lgkmcnt(1)
	v_mfma_f32_16x16x32_bf16 v[14:17], v[66:69], v[10:13], v[14:17]
	v_mfma_f32_16x16x32_bf16 v[18:21], v[70:73], v[10:13], v[18:21]
	v_mfma_f32_16x16x32_bf16 v[22:25], v[74:77], v[10:13], v[22:25]
	v_mfma_f32_16x16x32_bf16 v[26:29], v[42:45], v[10:13], v[26:29]
	v_mfma_f32_16x16x32_bf16 v[30:33], v[46:49], v[10:13], v[30:33]
	v_mfma_f32_16x16x32_bf16 v[34:37], v[50:53], v[10:13], v[34:37]
	v_mfma_f32_16x16x32_bf16 v[38:41], v[54:57], v[10:13], v[38:41]
	v_mfma_f32_16x16x32_bf16 v[6:9], v[58:61], v[10:13], v[6:9]
	ds_read_b128 v[10:13], v150 offset:832
	ds_read_b128 v[58:61], v97 offset:5024
	s_waitcnt lgkmcnt(1)
	v_mfma_f32_16x16x32_bf16 v[14:17], v[62:65], v[10:13], v[14:17]
	v_mfma_f32_16x16x32_bf16 v[18:21], v[66:69], v[10:13], v[18:21]
	v_mfma_f32_16x16x32_bf16 v[22:25], v[70:73], v[10:13], v[22:25]
	v_mfma_f32_16x16x32_bf16 v[26:29], v[74:77], v[10:13], v[26:29]
	v_mfma_f32_16x16x32_bf16 v[30:33], v[42:45], v[10:13], v[30:33]
	v_mfma_f32_16x16x32_bf16 v[34:37], v[46:49], v[10:13], v[34:37]
	v_mfma_f32_16x16x32_bf16 v[38:41], v[50:53], v[10:13], v[38:41]
	v_mfma_f32_16x16x32_bf16 v[6:9], v[54:57], v[10:13], v[6:9]
	ds_read_b128 v[10:13], v150 offset:896
	ds_read_b128 v[54:57], v97 offset:5088
	s_waitcnt lgkmcnt(1)
	v_mfma_f32_16x16x32_bf16 v[14:17], v[58:61], v[10:13], v[14:17]
	v_mfma_f32_16x16x32_bf16 v[18:21], v[62:65], v[10:13], v[18:21]
	v_mfma_f32_16x16x32_bf16 v[22:25], v[66:69], v[10:13], v[22:25]
	v_mfma_f32_16x16x32_bf16 v[26:29], v[70:73], v[10:13], v[26:29]
	v_mfma_f32_16x16x32_bf16 v[30:33], v[74:77], v[10:13], v[30:33]
	v_mfma_f32_16x16x32_bf16 v[34:37], v[42:45], v[10:13], v[34:37]
	v_mfma_f32_16x16x32_bf16 v[38:41], v[46:49], v[10:13], v[38:41]
	v_mfma_f32_16x16x32_bf16 v[6:9], v[50:53], v[10:13], v[6:9]
	ds_read_b128 v[10:13], v150 offset:960
	ds_read_b128 v[50:53], v97 offset:5152
	s_waitcnt lgkmcnt(1)
	v_mfma_f32_16x16x32_bf16 v[14:17], v[54:57], v[10:13], v[14:17]
	v_mfma_f32_16x16x32_bf16 v[18:21], v[58:61], v[10:13], v[18:21]
	v_mfma_f32_16x16x32_bf16 v[22:25], v[62:65], v[10:13], v[22:25]
	v_mfma_f32_16x16x32_bf16 v[26:29], v[66:69], v[10:13], v[26:29]
	v_mfma_f32_16x16x32_bf16 v[30:33], v[70:73], v[10:13], v[30:33]
	v_mfma_f32_16x16x32_bf16 v[34:37], v[74:77], v[10:13], v[34:37]
	v_mfma_f32_16x16x32_bf16 v[38:41], v[42:45], v[10:13], v[38:41]
	v_mfma_f32_16x16x32_bf16 v[6:9], v[46:49], v[10:13], v[6:9]
	ds_read_b128 v[10:13], v150 offset:1024
	ds_read_b128 v[46:49], v97 offset:5216
	s_waitcnt lgkmcnt(1)
	v_mfma_f32_16x16x32_bf16 v[14:17], v[50:53], v[10:13], v[14:17]
	v_mfma_f32_16x16x32_bf16 v[18:21], v[54:57], v[10:13], v[18:21]
	v_mfma_f32_16x16x32_bf16 v[22:25], v[58:61], v[10:13], v[22:25]
	v_mfma_f32_16x16x32_bf16 v[26:29], v[62:65], v[10:13], v[26:29]
	v_mfma_f32_16x16x32_bf16 v[30:33], v[66:69], v[10:13], v[30:33]
	v_mfma_f32_16x16x32_bf16 v[34:37], v[70:73], v[10:13], v[34:37]
	v_mfma_f32_16x16x32_bf16 v[38:41], v[74:77], v[10:13], v[38:41]
	v_mfma_f32_16x16x32_bf16 v[6:9], v[42:45], v[10:13], v[6:9]
	ds_read_b128 v[10:13], v150 offset:1088
	ds_read_b128 v[42:45], v97 offset:5280
	s_waitcnt lgkmcnt(1)
	v_mfma_f32_16x16x32_bf16 v[14:17], v[46:49], v[10:13], v[14:17]
	v_mfma_f32_16x16x32_bf16 v[18:21], v[50:53], v[10:13], v[18:21]
	v_mfma_f32_16x16x32_bf16 v[22:25], v[54:57], v[10:13], v[22:25]
	v_mfma_f32_16x16x32_bf16 v[26:29], v[58:61], v[10:13], v[26:29]
	v_mfma_f32_16x16x32_bf16 v[30:33], v[62:65], v[10:13], v[30:33]
	v_mfma_f32_16x16x32_bf16 v[34:37], v[66:69], v[10:13], v[34:37]
	v_mfma_f32_16x16x32_bf16 v[38:41], v[70:73], v[10:13], v[38:41]
	v_mfma_f32_16x16x32_bf16 v[6:9], v[74:77], v[10:13], v[6:9]
	ds_read_b128 v[10:13], v150 offset:1152
	ds_read_b128 v[74:77], v97 offset:5344
	s_waitcnt lgkmcnt(1)
	v_mfma_f32_16x16x32_bf16 v[14:17], v[42:45], v[10:13], v[14:17]
	v_mfma_f32_16x16x32_bf16 v[18:21], v[46:49], v[10:13], v[18:21]
	v_mfma_f32_16x16x32_bf16 v[22:25], v[50:53], v[10:13], v[22:25]
	v_mfma_f32_16x16x32_bf16 v[26:29], v[54:57], v[10:13], v[26:29]
	v_mfma_f32_16x16x32_bf16 v[30:33], v[58:61], v[10:13], v[30:33]
	v_mfma_f32_16x16x32_bf16 v[34:37], v[62:65], v[10:13], v[34:37]
	v_mfma_f32_16x16x32_bf16 v[38:41], v[66:69], v[10:13], v[38:41]
	v_mfma_f32_16x16x32_bf16 v[6:9], v[70:73], v[10:13], v[6:9]
	ds_read_b128 v[10:13], v150 offset:1216
	ds_read_b128 v[70:73], v97 offset:5408
	s_waitcnt lgkmcnt(1)
	v_mfma_f32_16x16x32_bf16 v[14:17], v[74:77], v[10:13], v[14:17]
	v_mfma_f32_16x16x32_bf16 v[18:21], v[42:45], v[10:13], v[18:21]
	v_mfma_f32_16x16x32_bf16 v[22:25], v[46:49], v[10:13], v[22:25]
	v_mfma_f32_16x16x32_bf16 v[26:29], v[50:53], v[10:13], v[26:29]
	v_mfma_f32_16x16x32_bf16 v[30:33], v[54:57], v[10:13], v[30:33]
	v_mfma_f32_16x16x32_bf16 v[34:37], v[58:61], v[10:13], v[34:37]
	v_mfma_f32_16x16x32_bf16 v[38:41], v[62:65], v[10:13], v[38:41]
	v_mfma_f32_16x16x32_bf16 v[6:9], v[66:69], v[10:13], v[6:9]
	ds_read_b128 v[10:13], v150 offset:1280
	ds_read_b128 v[66:69], v97 offset:5472
	s_waitcnt lgkmcnt(1)
	v_mfma_f32_16x16x32_bf16 v[14:17], v[70:73], v[10:13], v[14:17]
	v_mfma_f32_16x16x32_bf16 v[18:21], v[74:77], v[10:13], v[18:21]
	v_mfma_f32_16x16x32_bf16 v[22:25], v[42:45], v[10:13], v[22:25]
	v_mfma_f32_16x16x32_bf16 v[26:29], v[46:49], v[10:13], v[26:29]
	v_mfma_f32_16x16x32_bf16 v[30:33], v[50:53], v[10:13], v[30:33]
	v_mfma_f32_16x16x32_bf16 v[34:37], v[54:57], v[10:13], v[34:37]
	v_mfma_f32_16x16x32_bf16 v[38:41], v[58:61], v[10:13], v[38:41]
	v_mfma_f32_16x16x32_bf16 v[6:9], v[62:65], v[10:13], v[6:9]
	ds_read_b128 v[10:13], v150 offset:1344
	ds_read_b128 v[62:65], v97 offset:5536
	s_waitcnt lgkmcnt(1)
	v_mfma_f32_16x16x32_bf16 v[14:17], v[66:69], v[10:13], v[14:17]
	v_mfma_f32_16x16x32_bf16 v[18:21], v[70:73], v[10:13], v[18:21]
	v_mfma_f32_16x16x32_bf16 v[22:25], v[74:77], v[10:13], v[22:25]
	v_mfma_f32_16x16x32_bf16 v[26:29], v[42:45], v[10:13], v[26:29]
	v_mfma_f32_16x16x32_bf16 v[30:33], v[46:49], v[10:13], v[30:33]
	v_mfma_f32_16x16x32_bf16 v[34:37], v[50:53], v[10:13], v[34:37]
	v_mfma_f32_16x16x32_bf16 v[38:41], v[54:57], v[10:13], v[38:41]
	v_mfma_f32_16x16x32_bf16 v[6:9], v[58:61], v[10:13], v[6:9]
	ds_read_b128 v[10:13], v150 offset:1408
	ds_read_b128 v[58:61], v97 offset:5600
	s_waitcnt lgkmcnt(1)
	v_mfma_f32_16x16x32_bf16 v[14:17], v[62:65], v[10:13], v[14:17]
	v_mfma_f32_16x16x32_bf16 v[18:21], v[66:69], v[10:13], v[18:21]
	v_mfma_f32_16x16x32_bf16 v[22:25], v[70:73], v[10:13], v[22:25]
	v_mfma_f32_16x16x32_bf16 v[26:29], v[74:77], v[10:13], v[26:29]
	v_mfma_f32_16x16x32_bf16 v[30:33], v[42:45], v[10:13], v[30:33]
	v_mfma_f32_16x16x32_bf16 v[34:37], v[46:49], v[10:13], v[34:37]
	v_mfma_f32_16x16x32_bf16 v[38:41], v[50:53], v[10:13], v[38:41]
	v_mfma_f32_16x16x32_bf16 v[6:9], v[54:57], v[10:13], v[6:9]
	ds_read_b128 v[10:13], v150 offset:1472
	ds_read_b128 v[54:57], v97 offset:5664
	s_waitcnt lgkmcnt(1)
	v_mfma_f32_16x16x32_bf16 v[14:17], v[58:61], v[10:13], v[14:17]
	v_mfma_f32_16x16x32_bf16 v[18:21], v[62:65], v[10:13], v[18:21]
	v_mfma_f32_16x16x32_bf16 v[22:25], v[66:69], v[10:13], v[22:25]
	v_mfma_f32_16x16x32_bf16 v[26:29], v[70:73], v[10:13], v[26:29]
	v_mfma_f32_16x16x32_bf16 v[30:33], v[74:77], v[10:13], v[30:33]
	v_mfma_f32_16x16x32_bf16 v[34:37], v[42:45], v[10:13], v[34:37]
	v_mfma_f32_16x16x32_bf16 v[38:41], v[46:49], v[10:13], v[38:41]
	v_mfma_f32_16x16x32_bf16 v[6:9], v[50:53], v[10:13], v[6:9]
	ds_read_b128 v[10:13], v150 offset:1536
	ds_read_b128 v[50:53], v97 offset:5728
	s_waitcnt lgkmcnt(1)
	v_mfma_f32_16x16x32_bf16 v[14:17], v[54:57], v[10:13], v[14:17]
	v_mfma_f32_16x16x32_bf16 v[18:21], v[58:61], v[10:13], v[18:21]
	v_mfma_f32_16x16x32_bf16 v[22:25], v[62:65], v[10:13], v[22:25]
	v_mfma_f32_16x16x32_bf16 v[26:29], v[66:69], v[10:13], v[26:29]
	v_mfma_f32_16x16x32_bf16 v[30:33], v[70:73], v[10:13], v[30:33]
	v_mfma_f32_16x16x32_bf16 v[34:37], v[74:77], v[10:13], v[34:37]
	v_mfma_f32_16x16x32_bf16 v[38:41], v[42:45], v[10:13], v[38:41]
	v_mfma_f32_16x16x32_bf16 v[6:9], v[46:49], v[10:13], v[6:9]
	ds_read_b128 v[10:13], v150 offset:1600
	ds_read_b128 v[46:49], v97 offset:5792
	s_waitcnt lgkmcnt(1)
	v_mfma_f32_16x16x32_bf16 v[14:17], v[50:53], v[10:13], v[14:17]
	v_mfma_f32_16x16x32_bf16 v[18:21], v[54:57], v[10:13], v[18:21]
	v_mfma_f32_16x16x32_bf16 v[22:25], v[58:61], v[10:13], v[22:25]
	v_mfma_f32_16x16x32_bf16 v[26:29], v[62:65], v[10:13], v[26:29]
	v_mfma_f32_16x16x32_bf16 v[30:33], v[66:69], v[10:13], v[30:33]
	v_mfma_f32_16x16x32_bf16 v[34:37], v[70:73], v[10:13], v[34:37]
	v_mfma_f32_16x16x32_bf16 v[38:41], v[74:77], v[10:13], v[38:41]
	v_mfma_f32_16x16x32_bf16 v[6:9], v[42:45], v[10:13], v[6:9]
	ds_read_b128 v[10:13], v150 offset:1664
	ds_read_b128 v[42:45], v97 offset:5856
	s_waitcnt lgkmcnt(1)
	v_mfma_f32_16x16x32_bf16 v[14:17], v[46:49], v[10:13], v[14:17]
	v_mfma_f32_16x16x32_bf16 v[18:21], v[50:53], v[10:13], v[18:21]
	v_mfma_f32_16x16x32_bf16 v[22:25], v[54:57], v[10:13], v[22:25]
	v_mfma_f32_16x16x32_bf16 v[26:29], v[58:61], v[10:13], v[26:29]
	v_mfma_f32_16x16x32_bf16 v[30:33], v[62:65], v[10:13], v[30:33]
	v_mfma_f32_16x16x32_bf16 v[34:37], v[66:69], v[10:13], v[34:37]
	v_mfma_f32_16x16x32_bf16 v[38:41], v[70:73], v[10:13], v[38:41]
	v_mfma_f32_16x16x32_bf16 v[6:9], v[74:77], v[10:13], v[6:9]
	ds_read_b128 v[10:13], v150 offset:1728
	ds_read_b128 v[74:77], v97 offset:5920
	s_waitcnt lgkmcnt(1)
	v_mfma_f32_16x16x32_bf16 v[14:17], v[42:45], v[10:13], v[14:17]
	v_mfma_f32_16x16x32_bf16 v[18:21], v[46:49], v[10:13], v[18:21]
	v_mfma_f32_16x16x32_bf16 v[22:25], v[50:53], v[10:13], v[22:25]
	v_mfma_f32_16x16x32_bf16 v[26:29], v[54:57], v[10:13], v[26:29]
	v_mfma_f32_16x16x32_bf16 v[30:33], v[58:61], v[10:13], v[30:33]
	v_mfma_f32_16x16x32_bf16 v[34:37], v[62:65], v[10:13], v[34:37]
	v_mfma_f32_16x16x32_bf16 v[38:41], v[66:69], v[10:13], v[38:41]
	v_mfma_f32_16x16x32_bf16 v[6:9], v[70:73], v[10:13], v[6:9]
	ds_read_b128 v[10:13], v150 offset:1792
	ds_read_b128 v[70:73], v97 offset:5984
	s_waitcnt lgkmcnt(1)
	v_mfma_f32_16x16x32_bf16 v[14:17], v[74:77], v[10:13], v[14:17]
	v_mfma_f32_16x16x32_bf16 v[18:21], v[42:45], v[10:13], v[18:21]
	v_mfma_f32_16x16x32_bf16 v[22:25], v[46:49], v[10:13], v[22:25]
	v_mfma_f32_16x16x32_bf16 v[26:29], v[50:53], v[10:13], v[26:29]
	v_mfma_f32_16x16x32_bf16 v[30:33], v[54:57], v[10:13], v[30:33]
	v_mfma_f32_16x16x32_bf16 v[34:37], v[58:61], v[10:13], v[34:37]
	v_mfma_f32_16x16x32_bf16 v[38:41], v[62:65], v[10:13], v[38:41]
	v_mfma_f32_16x16x32_bf16 v[6:9], v[66:69], v[10:13], v[6:9]
	ds_read_b128 v[10:13], v150 offset:1856
	ds_read_b128 v[66:69], v97 offset:6048
	s_waitcnt lgkmcnt(1)
	v_mfma_f32_16x16x32_bf16 v[14:17], v[70:73], v[10:13], v[14:17]
	v_mfma_f32_16x16x32_bf16 v[18:21], v[74:77], v[10:13], v[18:21]
	v_mfma_f32_16x16x32_bf16 v[22:25], v[42:45], v[10:13], v[22:25]
	v_mfma_f32_16x16x32_bf16 v[26:29], v[46:49], v[10:13], v[26:29]
	v_mfma_f32_16x16x32_bf16 v[30:33], v[50:53], v[10:13], v[30:33]
	v_mfma_f32_16x16x32_bf16 v[34:37], v[54:57], v[10:13], v[34:37]
	v_mfma_f32_16x16x32_bf16 v[38:41], v[58:61], v[10:13], v[38:41]
	v_mfma_f32_16x16x32_bf16 v[6:9], v[62:65], v[10:13], v[6:9]
	ds_read_b128 v[10:13], v150 offset:1920
	ds_read_b128 v[62:65], v97 offset:6112
	s_waitcnt lgkmcnt(1)
	v_mfma_f32_16x16x32_bf16 v[14:17], v[66:69], v[10:13], v[14:17]
	v_mfma_f32_16x16x32_bf16 v[18:21], v[70:73], v[10:13], v[18:21]
	v_mfma_f32_16x16x32_bf16 v[22:25], v[74:77], v[10:13], v[22:25]
	v_mfma_f32_16x16x32_bf16 v[26:29], v[42:45], v[10:13], v[26:29]
	v_mfma_f32_16x16x32_bf16 v[30:33], v[46:49], v[10:13], v[30:33]
	v_mfma_f32_16x16x32_bf16 v[34:37], v[50:53], v[10:13], v[34:37]
	v_mfma_f32_16x16x32_bf16 v[38:41], v[54:57], v[10:13], v[38:41]
	v_mfma_f32_16x16x32_bf16 v[6:9], v[58:61], v[10:13], v[6:9]
	ds_read_b128 v[10:13], v150 offset:1984
	ds_read_b128 v[58:61], v97 offset:6176
	s_waitcnt lgkmcnt(1)
	v_mfma_f32_16x16x32_bf16 v[14:17], v[62:65], v[10:13], v[14:17]
	v_mfma_f32_16x16x32_bf16 v[18:21], v[66:69], v[10:13], v[18:21]
	v_mfma_f32_16x16x32_bf16 v[22:25], v[70:73], v[10:13], v[22:25]
	v_mfma_f32_16x16x32_bf16 v[26:29], v[74:77], v[10:13], v[26:29]
	v_mfma_f32_16x16x32_bf16 v[30:33], v[42:45], v[10:13], v[30:33]
	v_mfma_f32_16x16x32_bf16 v[34:37], v[46:49], v[10:13], v[34:37]
	v_mfma_f32_16x16x32_bf16 v[38:41], v[50:53], v[10:13], v[38:41]
	v_mfma_f32_16x16x32_bf16 v[6:9], v[54:57], v[10:13], v[6:9]
	ds_read_b128 v[10:13], v150 offset:2048
	ds_read_b128 v[54:57], v97 offset:6240
	s_waitcnt lgkmcnt(1)
	v_mfma_f32_16x16x32_bf16 v[14:17], v[58:61], v[10:13], v[14:17]
	v_mfma_f32_16x16x32_bf16 v[18:21], v[62:65], v[10:13], v[18:21]
	v_mfma_f32_16x16x32_bf16 v[22:25], v[66:69], v[10:13], v[22:25]
	v_mfma_f32_16x16x32_bf16 v[26:29], v[70:73], v[10:13], v[26:29]
	v_mfma_f32_16x16x32_bf16 v[30:33], v[74:77], v[10:13], v[30:33]
	v_mfma_f32_16x16x32_bf16 v[34:37], v[42:45], v[10:13], v[34:37]
	v_mfma_f32_16x16x32_bf16 v[38:41], v[46:49], v[10:13], v[38:41]
	v_mfma_f32_16x16x32_bf16 v[6:9], v[50:53], v[10:13], v[6:9]
	ds_read_b128 v[10:13], v150 offset:2112
	ds_read_b128 v[50:53], v97 offset:6304
	s_waitcnt lgkmcnt(1)
	v_mfma_f32_16x16x32_bf16 v[14:17], v[54:57], v[10:13], v[14:17]
	v_mfma_f32_16x16x32_bf16 v[18:21], v[58:61], v[10:13], v[18:21]
	v_mfma_f32_16x16x32_bf16 v[22:25], v[62:65], v[10:13], v[22:25]
	v_mfma_f32_16x16x32_bf16 v[26:29], v[66:69], v[10:13], v[26:29]
	v_mfma_f32_16x16x32_bf16 v[30:33], v[70:73], v[10:13], v[30:33]
	v_mfma_f32_16x16x32_bf16 v[34:37], v[74:77], v[10:13], v[34:37]
	v_mfma_f32_16x16x32_bf16 v[38:41], v[42:45], v[10:13], v[38:41]
	v_mfma_f32_16x16x32_bf16 v[6:9], v[46:49], v[10:13], v[6:9]
	ds_read_b128 v[10:13], v150 offset:2176
	ds_read_b128 v[46:49], v97 offset:6368
	s_waitcnt lgkmcnt(1)
	v_mfma_f32_16x16x32_bf16 v[14:17], v[50:53], v[10:13], v[14:17]
	v_mfma_f32_16x16x32_bf16 v[18:21], v[54:57], v[10:13], v[18:21]
	v_mfma_f32_16x16x32_bf16 v[22:25], v[58:61], v[10:13], v[22:25]
	v_mfma_f32_16x16x32_bf16 v[26:29], v[62:65], v[10:13], v[26:29]
	v_mfma_f32_16x16x32_bf16 v[30:33], v[66:69], v[10:13], v[30:33]
	v_mfma_f32_16x16x32_bf16 v[34:37], v[70:73], v[10:13], v[34:37]
	v_mfma_f32_16x16x32_bf16 v[38:41], v[74:77], v[10:13], v[38:41]
	v_mfma_f32_16x16x32_bf16 v[6:9], v[42:45], v[10:13], v[6:9]
	ds_read_b128 v[10:13], v150 offset:2240
	ds_read_b128 v[42:45], v97 offset:6432
	s_waitcnt lgkmcnt(1)
	v_mfma_f32_16x16x32_bf16 v[14:17], v[46:49], v[10:13], v[14:17]
	v_mfma_f32_16x16x32_bf16 v[18:21], v[50:53], v[10:13], v[18:21]
	v_mfma_f32_16x16x32_bf16 v[22:25], v[54:57], v[10:13], v[22:25]
	v_mfma_f32_16x16x32_bf16 v[26:29], v[58:61], v[10:13], v[26:29]
	v_mfma_f32_16x16x32_bf16 v[30:33], v[62:65], v[10:13], v[30:33]
	v_mfma_f32_16x16x32_bf16 v[34:37], v[66:69], v[10:13], v[34:37]
	v_mfma_f32_16x16x32_bf16 v[38:41], v[70:73], v[10:13], v[38:41]
	v_mfma_f32_16x16x32_bf16 v[6:9], v[74:77], v[10:13], v[6:9]
	ds_read_b128 v[10:13], v150 offset:2304
	ds_read_b128 v[74:77], v97 offset:6496
	s_waitcnt lgkmcnt(1)
	v_mfma_f32_16x16x32_bf16 v[14:17], v[42:45], v[10:13], v[14:17]
	v_mfma_f32_16x16x32_bf16 v[18:21], v[46:49], v[10:13], v[18:21]
	v_mfma_f32_16x16x32_bf16 v[22:25], v[50:53], v[10:13], v[22:25]
	v_mfma_f32_16x16x32_bf16 v[26:29], v[54:57], v[10:13], v[26:29]
	v_mfma_f32_16x16x32_bf16 v[30:33], v[58:61], v[10:13], v[30:33]
	v_mfma_f32_16x16x32_bf16 v[34:37], v[62:65], v[10:13], v[34:37]
	v_mfma_f32_16x16x32_bf16 v[38:41], v[66:69], v[10:13], v[38:41]
	v_mfma_f32_16x16x32_bf16 v[6:9], v[70:73], v[10:13], v[6:9]
	ds_read_b128 v[10:13], v150 offset:2368
	ds_read_b128 v[70:73], v97 offset:6560
	s_waitcnt lgkmcnt(1)
	v_mfma_f32_16x16x32_bf16 v[14:17], v[74:77], v[10:13], v[14:17]
	v_mfma_f32_16x16x32_bf16 v[18:21], v[42:45], v[10:13], v[18:21]
	v_mfma_f32_16x16x32_bf16 v[22:25], v[46:49], v[10:13], v[22:25]
	v_mfma_f32_16x16x32_bf16 v[26:29], v[50:53], v[10:13], v[26:29]
	v_mfma_f32_16x16x32_bf16 v[30:33], v[54:57], v[10:13], v[30:33]
	v_mfma_f32_16x16x32_bf16 v[34:37], v[58:61], v[10:13], v[34:37]
	v_mfma_f32_16x16x32_bf16 v[38:41], v[62:65], v[10:13], v[38:41]
	v_mfma_f32_16x16x32_bf16 v[6:9], v[66:69], v[10:13], v[6:9]
	ds_read_b128 v[10:13], v150 offset:2432
	ds_read_b128 v[66:69], v97 offset:6624
	s_waitcnt lgkmcnt(1)
	v_mfma_f32_16x16x32_bf16 v[14:17], v[70:73], v[10:13], v[14:17]
	v_mfma_f32_16x16x32_bf16 v[18:21], v[74:77], v[10:13], v[18:21]
	v_mfma_f32_16x16x32_bf16 v[22:25], v[42:45], v[10:13], v[22:25]
	v_mfma_f32_16x16x32_bf16 v[26:29], v[46:49], v[10:13], v[26:29]
	v_mfma_f32_16x16x32_bf16 v[30:33], v[50:53], v[10:13], v[30:33]
	v_mfma_f32_16x16x32_bf16 v[34:37], v[54:57], v[10:13], v[34:37]
	v_mfma_f32_16x16x32_bf16 v[38:41], v[58:61], v[10:13], v[38:41]
	v_mfma_f32_16x16x32_bf16 v[6:9], v[62:65], v[10:13], v[6:9]
	ds_read_b128 v[10:13], v150 offset:2496
	ds_read_b128 v[62:65], v97 offset:6688
	s_waitcnt lgkmcnt(1)
	v_mfma_f32_16x16x32_bf16 v[14:17], v[66:69], v[10:13], v[14:17]
	v_mfma_f32_16x16x32_bf16 v[18:21], v[70:73], v[10:13], v[18:21]
	v_mfma_f32_16x16x32_bf16 v[22:25], v[74:77], v[10:13], v[22:25]
	v_mfma_f32_16x16x32_bf16 v[26:29], v[42:45], v[10:13], v[26:29]
	v_mfma_f32_16x16x32_bf16 v[30:33], v[46:49], v[10:13], v[30:33]
	v_mfma_f32_16x16x32_bf16 v[34:37], v[50:53], v[10:13], v[34:37]
	v_mfma_f32_16x16x32_bf16 v[38:41], v[54:57], v[10:13], v[38:41]
	v_mfma_f32_16x16x32_bf16 v[6:9], v[58:61], v[10:13], v[6:9]
	ds_read_b128 v[10:13], v150 offset:2560
	ds_read_b128 v[58:61], v97 offset:6752
	s_waitcnt lgkmcnt(1)
	v_mfma_f32_16x16x32_bf16 v[14:17], v[62:65], v[10:13], v[14:17]
	v_mfma_f32_16x16x32_bf16 v[18:21], v[66:69], v[10:13], v[18:21]
	v_mfma_f32_16x16x32_bf16 v[22:25], v[70:73], v[10:13], v[22:25]
	v_mfma_f32_16x16x32_bf16 v[26:29], v[74:77], v[10:13], v[26:29]
	v_mfma_f32_16x16x32_bf16 v[30:33], v[42:45], v[10:13], v[30:33]
	v_mfma_f32_16x16x32_bf16 v[34:37], v[46:49], v[10:13], v[34:37]
	v_mfma_f32_16x16x32_bf16 v[38:41], v[50:53], v[10:13], v[38:41]
	v_mfma_f32_16x16x32_bf16 v[6:9], v[54:57], v[10:13], v[6:9]
	ds_read_b128 v[10:13], v150 offset:2624
	ds_read_b128 v[54:57], v97 offset:6816
	s_waitcnt lgkmcnt(1)
	v_mfma_f32_16x16x32_bf16 v[14:17], v[58:61], v[10:13], v[14:17]
	v_mfma_f32_16x16x32_bf16 v[18:21], v[62:65], v[10:13], v[18:21]
	v_mfma_f32_16x16x32_bf16 v[22:25], v[66:69], v[10:13], v[22:25]
	v_mfma_f32_16x16x32_bf16 v[26:29], v[70:73], v[10:13], v[26:29]
	v_mfma_f32_16x16x32_bf16 v[30:33], v[74:77], v[10:13], v[30:33]
	v_mfma_f32_16x16x32_bf16 v[34:37], v[42:45], v[10:13], v[34:37]
	v_mfma_f32_16x16x32_bf16 v[38:41], v[46:49], v[10:13], v[38:41]
	v_mfma_f32_16x16x32_bf16 v[6:9], v[50:53], v[10:13], v[6:9]
	ds_read_b128 v[10:13], v150 offset:2688
	ds_read_b128 v[50:53], v97 offset:6880
	s_waitcnt lgkmcnt(1)
	v_mfma_f32_16x16x32_bf16 v[14:17], v[54:57], v[10:13], v[14:17]
	v_mfma_f32_16x16x32_bf16 v[18:21], v[58:61], v[10:13], v[18:21]
	v_mfma_f32_16x16x32_bf16 v[22:25], v[62:65], v[10:13], v[22:25]
	v_mfma_f32_16x16x32_bf16 v[26:29], v[66:69], v[10:13], v[26:29]
	v_mfma_f32_16x16x32_bf16 v[30:33], v[70:73], v[10:13], v[30:33]
	v_mfma_f32_16x16x32_bf16 v[34:37], v[74:77], v[10:13], v[34:37]
	v_mfma_f32_16x16x32_bf16 v[38:41], v[42:45], v[10:13], v[38:41]
	v_mfma_f32_16x16x32_bf16 v[6:9], v[46:49], v[10:13], v[6:9]
	ds_read_b128 v[10:13], v150 offset:2752
	ds_read_b128 v[46:49], v97 offset:6944
	s_waitcnt lgkmcnt(1)
	v_mfma_f32_16x16x32_bf16 v[14:17], v[50:53], v[10:13], v[14:17]
	v_mfma_f32_16x16x32_bf16 v[18:21], v[54:57], v[10:13], v[18:21]
	v_mfma_f32_16x16x32_bf16 v[22:25], v[58:61], v[10:13], v[22:25]
	v_mfma_f32_16x16x32_bf16 v[26:29], v[62:65], v[10:13], v[26:29]
	v_mfma_f32_16x16x32_bf16 v[30:33], v[66:69], v[10:13], v[30:33]
	v_mfma_f32_16x16x32_bf16 v[34:37], v[70:73], v[10:13], v[34:37]
	v_mfma_f32_16x16x32_bf16 v[38:41], v[74:77], v[10:13], v[38:41]
	v_mfma_f32_16x16x32_bf16 v[6:9], v[42:45], v[10:13], v[6:9]
	ds_read_b128 v[10:13], v150 offset:2816
	ds_read_b128 v[42:45], v97 offset:7008
	s_waitcnt lgkmcnt(1)
	v_mfma_f32_16x16x32_bf16 v[14:17], v[46:49], v[10:13], v[14:17]
	v_mfma_f32_16x16x32_bf16 v[18:21], v[50:53], v[10:13], v[18:21]
	v_mfma_f32_16x16x32_bf16 v[22:25], v[54:57], v[10:13], v[22:25]
	v_mfma_f32_16x16x32_bf16 v[26:29], v[58:61], v[10:13], v[26:29]
	v_mfma_f32_16x16x32_bf16 v[30:33], v[62:65], v[10:13], v[30:33]
	v_mfma_f32_16x16x32_bf16 v[34:37], v[66:69], v[10:13], v[34:37]
	v_mfma_f32_16x16x32_bf16 v[38:41], v[70:73], v[10:13], v[38:41]
	v_mfma_f32_16x16x32_bf16 v[6:9], v[74:77], v[10:13], v[6:9]
	ds_read_b128 v[10:13], v150 offset:2880
	ds_read_b128 v[74:77], v97 offset:7072
	s_waitcnt lgkmcnt(1)
	v_mfma_f32_16x16x32_bf16 v[14:17], v[42:45], v[10:13], v[14:17]
	v_mfma_f32_16x16x32_bf16 v[18:21], v[46:49], v[10:13], v[18:21]
	v_mfma_f32_16x16x32_bf16 v[22:25], v[50:53], v[10:13], v[22:25]
	v_mfma_f32_16x16x32_bf16 v[26:29], v[54:57], v[10:13], v[26:29]
	v_mfma_f32_16x16x32_bf16 v[30:33], v[58:61], v[10:13], v[30:33]
	v_mfma_f32_16x16x32_bf16 v[34:37], v[62:65], v[10:13], v[34:37]
	v_mfma_f32_16x16x32_bf16 v[38:41], v[66:69], v[10:13], v[38:41]
	v_mfma_f32_16x16x32_bf16 v[6:9], v[70:73], v[10:13], v[6:9]
	ds_read_b128 v[10:13], v150 offset:2944
	ds_read_b128 v[70:73], v97 offset:7136
	s_waitcnt lgkmcnt(1)
	v_mfma_f32_16x16x32_bf16 v[14:17], v[74:77], v[10:13], v[14:17]
	v_mfma_f32_16x16x32_bf16 v[18:21], v[42:45], v[10:13], v[18:21]
	v_mfma_f32_16x16x32_bf16 v[22:25], v[46:49], v[10:13], v[22:25]
	v_mfma_f32_16x16x32_bf16 v[26:29], v[50:53], v[10:13], v[26:29]
	v_mfma_f32_16x16x32_bf16 v[30:33], v[54:57], v[10:13], v[30:33]
	v_mfma_f32_16x16x32_bf16 v[34:37], v[58:61], v[10:13], v[34:37]
	v_mfma_f32_16x16x32_bf16 v[38:41], v[62:65], v[10:13], v[38:41]
	v_mfma_f32_16x16x32_bf16 v[6:9], v[66:69], v[10:13], v[6:9]
	ds_read_b128 v[10:13], v150 offset:3008
	ds_read_b128 v[66:69], v97 offset:7200
	s_waitcnt lgkmcnt(1)
	v_mfma_f32_16x16x32_bf16 v[14:17], v[70:73], v[10:13], v[14:17]
	v_mfma_f32_16x16x32_bf16 v[18:21], v[74:77], v[10:13], v[18:21]
	v_mfma_f32_16x16x32_bf16 v[22:25], v[42:45], v[10:13], v[22:25]
	v_mfma_f32_16x16x32_bf16 v[26:29], v[46:49], v[10:13], v[26:29]
	v_mfma_f32_16x16x32_bf16 v[30:33], v[50:53], v[10:13], v[30:33]
	v_mfma_f32_16x16x32_bf16 v[34:37], v[54:57], v[10:13], v[34:37]
	v_mfma_f32_16x16x32_bf16 v[38:41], v[58:61], v[10:13], v[38:41]
	v_mfma_f32_16x16x32_bf16 v[6:9], v[62:65], v[10:13], v[6:9]
	ds_read_b128 v[10:13], v150 offset:3072
	ds_read_b128 v[62:65], v97 offset:7264
	s_waitcnt lgkmcnt(1)
	v_mfma_f32_16x16x32_bf16 v[14:17], v[66:69], v[10:13], v[14:17]
	v_mfma_f32_16x16x32_bf16 v[18:21], v[70:73], v[10:13], v[18:21]
	v_mfma_f32_16x16x32_bf16 v[22:25], v[74:77], v[10:13], v[22:25]
	v_mfma_f32_16x16x32_bf16 v[26:29], v[42:45], v[10:13], v[26:29]
	v_mfma_f32_16x16x32_bf16 v[30:33], v[46:49], v[10:13], v[30:33]
	v_mfma_f32_16x16x32_bf16 v[34:37], v[50:53], v[10:13], v[34:37]
	v_mfma_f32_16x16x32_bf16 v[38:41], v[54:57], v[10:13], v[38:41]
	v_mfma_f32_16x16x32_bf16 v[6:9], v[58:61], v[10:13], v[6:9]
	ds_read_b128 v[10:13], v150 offset:3136
	ds_read_b128 v[58:61], v97 offset:7328
	s_waitcnt lgkmcnt(1)
	v_mfma_f32_16x16x32_bf16 v[14:17], v[62:65], v[10:13], v[14:17]
	v_mfma_f32_16x16x32_bf16 v[18:21], v[66:69], v[10:13], v[18:21]
	v_mfma_f32_16x16x32_bf16 v[22:25], v[70:73], v[10:13], v[22:25]
	v_mfma_f32_16x16x32_bf16 v[26:29], v[74:77], v[10:13], v[26:29]
	v_mfma_f32_16x16x32_bf16 v[30:33], v[42:45], v[10:13], v[30:33]
	v_mfma_f32_16x16x32_bf16 v[34:37], v[46:49], v[10:13], v[34:37]
	v_mfma_f32_16x16x32_bf16 v[38:41], v[50:53], v[10:13], v[38:41]
	v_mfma_f32_16x16x32_bf16 v[6:9], v[54:57], v[10:13], v[6:9]
	ds_read_b128 v[10:13], v150 offset:3200
	ds_read_b128 v[54:57], v97 offset:7392
	s_waitcnt lgkmcnt(1)
	v_mfma_f32_16x16x32_bf16 v[14:17], v[58:61], v[10:13], v[14:17]
	v_mfma_f32_16x16x32_bf16 v[18:21], v[62:65], v[10:13], v[18:21]
	v_mfma_f32_16x16x32_bf16 v[22:25], v[66:69], v[10:13], v[22:25]
	v_mfma_f32_16x16x32_bf16 v[26:29], v[70:73], v[10:13], v[26:29]
	v_mfma_f32_16x16x32_bf16 v[30:33], v[74:77], v[10:13], v[30:33]
	v_mfma_f32_16x16x32_bf16 v[34:37], v[42:45], v[10:13], v[34:37]
	v_mfma_f32_16x16x32_bf16 v[38:41], v[46:49], v[10:13], v[38:41]
	v_mfma_f32_16x16x32_bf16 v[6:9], v[50:53], v[10:13], v[6:9]
	ds_read_b128 v[10:13], v150 offset:3264
	ds_read_b128 v[50:53], v97 offset:7456
	s_waitcnt lgkmcnt(1)
	v_mfma_f32_16x16x32_bf16 v[14:17], v[54:57], v[10:13], v[14:17]
	v_mfma_f32_16x16x32_bf16 v[18:21], v[58:61], v[10:13], v[18:21]
	v_mfma_f32_16x16x32_bf16 v[22:25], v[62:65], v[10:13], v[22:25]
	v_mfma_f32_16x16x32_bf16 v[26:29], v[66:69], v[10:13], v[26:29]
	v_mfma_f32_16x16x32_bf16 v[30:33], v[70:73], v[10:13], v[30:33]
	v_mfma_f32_16x16x32_bf16 v[34:37], v[74:77], v[10:13], v[34:37]
	v_mfma_f32_16x16x32_bf16 v[38:41], v[42:45], v[10:13], v[38:41]
	v_mfma_f32_16x16x32_bf16 v[6:9], v[46:49], v[10:13], v[6:9]
	ds_read_b128 v[10:13], v150 offset:3328
	ds_read_b128 v[46:49], v97 offset:7520
	s_waitcnt lgkmcnt(1)
	v_mfma_f32_16x16x32_bf16 v[14:17], v[50:53], v[10:13], v[14:17]
	v_mfma_f32_16x16x32_bf16 v[18:21], v[54:57], v[10:13], v[18:21]
	v_mfma_f32_16x16x32_bf16 v[22:25], v[58:61], v[10:13], v[22:25]
	v_mfma_f32_16x16x32_bf16 v[26:29], v[62:65], v[10:13], v[26:29]
	v_mfma_f32_16x16x32_bf16 v[30:33], v[66:69], v[10:13], v[30:33]
	v_mfma_f32_16x16x32_bf16 v[34:37], v[70:73], v[10:13], v[34:37]
	v_mfma_f32_16x16x32_bf16 v[38:41], v[74:77], v[10:13], v[38:41]
	v_mfma_f32_16x16x32_bf16 v[6:9], v[42:45], v[10:13], v[6:9]
	ds_read_b128 v[10:13], v150 offset:3392
	ds_read_b128 v[42:45], v97 offset:7584
	s_waitcnt lgkmcnt(1)
	v_mfma_f32_16x16x32_bf16 v[14:17], v[46:49], v[10:13], v[14:17]
	v_mfma_f32_16x16x32_bf16 v[18:21], v[50:53], v[10:13], v[18:21]
	v_mfma_f32_16x16x32_bf16 v[22:25], v[54:57], v[10:13], v[22:25]
	v_mfma_f32_16x16x32_bf16 v[26:29], v[58:61], v[10:13], v[26:29]
	v_mfma_f32_16x16x32_bf16 v[30:33], v[62:65], v[10:13], v[30:33]
	v_mfma_f32_16x16x32_bf16 v[34:37], v[66:69], v[10:13], v[34:37]
	v_mfma_f32_16x16x32_bf16 v[38:41], v[70:73], v[10:13], v[38:41]
	v_mfma_f32_16x16x32_bf16 v[6:9], v[74:77], v[10:13], v[6:9]
	ds_read_b128 v[10:13], v150 offset:3456
	ds_read_b128 v[74:77], v97 offset:7648
	s_waitcnt lgkmcnt(1)
	v_mfma_f32_16x16x32_bf16 v[14:17], v[42:45], v[10:13], v[14:17]
	v_mfma_f32_16x16x32_bf16 v[18:21], v[46:49], v[10:13], v[18:21]
	v_mfma_f32_16x16x32_bf16 v[22:25], v[50:53], v[10:13], v[22:25]
	v_mfma_f32_16x16x32_bf16 v[26:29], v[54:57], v[10:13], v[26:29]
	v_mfma_f32_16x16x32_bf16 v[30:33], v[58:61], v[10:13], v[30:33]
	v_mfma_f32_16x16x32_bf16 v[34:37], v[62:65], v[10:13], v[34:37]
	v_mfma_f32_16x16x32_bf16 v[38:41], v[66:69], v[10:13], v[38:41]
	v_mfma_f32_16x16x32_bf16 v[6:9], v[70:73], v[10:13], v[6:9]
	ds_read_b128 v[10:13], v150 offset:3520
	ds_read_b128 v[70:73], v97 offset:7712
	s_waitcnt lgkmcnt(1)
	v_mfma_f32_16x16x32_bf16 v[14:17], v[74:77], v[10:13], v[14:17]
	v_mfma_f32_16x16x32_bf16 v[18:21], v[42:45], v[10:13], v[18:21]
	v_mfma_f32_16x16x32_bf16 v[22:25], v[46:49], v[10:13], v[22:25]
	v_mfma_f32_16x16x32_bf16 v[26:29], v[50:53], v[10:13], v[26:29]
	v_mfma_f32_16x16x32_bf16 v[30:33], v[54:57], v[10:13], v[30:33]
	v_mfma_f32_16x16x32_bf16 v[34:37], v[58:61], v[10:13], v[34:37]
	v_mfma_f32_16x16x32_bf16 v[38:41], v[62:65], v[10:13], v[38:41]
	v_mfma_f32_16x16x32_bf16 v[6:9], v[66:69], v[10:13], v[6:9]
	ds_read_b128 v[10:13], v150 offset:3584
	ds_read_b128 v[66:69], v97 offset:7776
	s_waitcnt lgkmcnt(1)
	v_mfma_f32_16x16x32_bf16 v[14:17], v[70:73], v[10:13], v[14:17]
	v_mfma_f32_16x16x32_bf16 v[18:21], v[74:77], v[10:13], v[18:21]
	v_mfma_f32_16x16x32_bf16 v[22:25], v[42:45], v[10:13], v[22:25]
	v_mfma_f32_16x16x32_bf16 v[26:29], v[46:49], v[10:13], v[26:29]
	v_mfma_f32_16x16x32_bf16 v[30:33], v[50:53], v[10:13], v[30:33]
	v_mfma_f32_16x16x32_bf16 v[34:37], v[54:57], v[10:13], v[34:37]
	v_mfma_f32_16x16x32_bf16 v[38:41], v[58:61], v[10:13], v[38:41]
	v_mfma_f32_16x16x32_bf16 v[6:9], v[62:65], v[10:13], v[6:9]
	ds_read_b128 v[10:13], v150 offset:3648
	ds_read_b128 v[62:65], v97 offset:7840
	s_waitcnt lgkmcnt(1)
	v_mfma_f32_16x16x32_bf16 v[14:17], v[66:69], v[10:13], v[14:17]
	v_mfma_f32_16x16x32_bf16 v[18:21], v[70:73], v[10:13], v[18:21]
	v_mfma_f32_16x16x32_bf16 v[22:25], v[74:77], v[10:13], v[22:25]
	v_mfma_f32_16x16x32_bf16 v[26:29], v[42:45], v[10:13], v[26:29]
	v_mfma_f32_16x16x32_bf16 v[30:33], v[46:49], v[10:13], v[30:33]
	v_mfma_f32_16x16x32_bf16 v[34:37], v[50:53], v[10:13], v[34:37]
	v_mfma_f32_16x16x32_bf16 v[38:41], v[54:57], v[10:13], v[38:41]
	v_mfma_f32_16x16x32_bf16 v[10:13], v[58:61], v[10:13], v[6:9]
	ds_read_b128 v[58:61], v150 offset:3712
	s_nop 1
	ds_read_b128 v[6:9], v97 offset:7904
	s_waitcnt lgkmcnt(1)
	v_mfma_f32_16x16x32_bf16 v[14:17], v[62:65], v[58:61], v[14:17]
	v_mfma_f32_16x16x32_bf16 v[18:21], v[66:69], v[58:61], v[18:21]
	v_mfma_f32_16x16x32_bf16 v[22:25], v[70:73], v[58:61], v[22:25]
	v_mfma_f32_16x16x32_bf16 v[26:29], v[74:77], v[58:61], v[26:29]
	v_mfma_f32_16x16x32_bf16 v[30:33], v[42:45], v[58:61], v[30:33]
	v_mfma_f32_16x16x32_bf16 v[34:37], v[46:49], v[58:61], v[34:37]
	v_mfma_f32_16x16x32_bf16 v[38:41], v[50:53], v[58:61], v[38:41]
	v_mfma_f32_16x16x32_bf16 v[54:57], v[54:57], v[58:61], v[10:13]
	ds_read_b128 v[58:61], v150 offset:3776
	s_nop 1
	ds_read_b128 v[10:13], v97 offset:7968
	s_waitcnt lgkmcnt(1)
	v_mfma_f32_16x16x32_bf16 v[50:53], v[50:53], v[58:61], v[54:57]
	s_nop 2
	ds_read_b128 v[54:57], v150 offset:3840
	v_mfma_f32_16x16x32_bf16 v[14:17], v[6:9], v[58:61], v[14:17]
	v_mfma_f32_16x16x32_bf16 v[18:21], v[62:65], v[58:61], v[18:21]
	v_mfma_f32_16x16x32_bf16 v[22:25], v[66:69], v[58:61], v[22:25]
	v_mfma_f32_16x16x32_bf16 v[26:29], v[70:73], v[58:61], v[26:29]
	v_mfma_f32_16x16x32_bf16 v[30:33], v[74:77], v[58:61], v[30:33]
	v_mfma_f32_16x16x32_bf16 v[34:37], v[42:45], v[58:61], v[34:37]
	v_mfma_f32_16x16x32_bf16 v[38:41], v[46:49], v[58:61], v[38:41]
	s_waitcnt lgkmcnt(0)
	v_mfma_f32_16x16x32_bf16 v[58:61], v[10:13], v[54:57], v[14:17]
	s_nop 2
	ds_read_b128 v[14:17], v97 offset:8032
	v_mfma_f32_16x16x32_bf16 v[46:49], v[46:49], v[54:57], v[50:53]
	s_nop 2
	ds_read_b128 v[50:53], v150 offset:3904
	v_mfma_f32_16x16x32_bf16 v[18:21], v[6:9], v[54:57], v[18:21]
	v_mfma_f32_16x16x32_bf16 v[22:25], v[62:65], v[54:57], v[22:25]
	v_mfma_f32_16x16x32_bf16 v[26:29], v[66:69], v[54:57], v[26:29]
	v_mfma_f32_16x16x32_bf16 v[30:33], v[70:73], v[54:57], v[30:33]
	v_mfma_f32_16x16x32_bf16 v[34:37], v[74:77], v[54:57], v[34:37]
	v_mfma_f32_16x16x32_bf16 v[38:41], v[42:45], v[54:57], v[38:41]
	s_waitcnt lgkmcnt(0)
	v_mfma_f32_16x16x32_bf16 v[54:57], v[14:17], v[50:53], v[58:61]
	v_mfma_f32_16x16x32_bf16 v[58:61], v[10:13], v[50:53], v[18:21]
	s_nop 2
	ds_read_b128 v[18:21], v97 offset:8096
	v_mfma_f32_16x16x32_bf16 v[42:45], v[42:45], v[50:53], v[46:49]
	s_nop 2
	ds_read_b128 v[46:49], v150 offset:3968
	v_mfma_f32_16x16x32_bf16 v[22:25], v[6:9], v[50:53], v[22:25]
	v_mfma_f32_16x16x32_bf16 v[26:29], v[62:65], v[50:53], v[26:29]
	v_mfma_f32_16x16x32_bf16 v[30:33], v[66:69], v[50:53], v[30:33]
	v_mfma_f32_16x16x32_bf16 v[34:37], v[70:73], v[50:53], v[34:37]
	v_mfma_f32_16x16x32_bf16 v[38:41], v[74:77], v[50:53], v[38:41]
	s_waitcnt lgkmcnt(0)
	v_mfma_f32_16x16x32_bf16 v[50:53], v[18:21], v[46:49], v[54:57]
	v_mfma_f32_16x16x32_bf16 v[54:57], v[14:17], v[46:49], v[58:61]
	v_mfma_f32_16x16x32_bf16 v[58:61], v[10:13], v[46:49], v[22:25]
	v_mfma_f32_16x16x32_bf16 v[26:29], v[6:9], v[46:49], v[26:29]
	s_nop 1
	ds_read_b128 v[22:25], v97 offset:8160
	v_mfma_f32_16x16x32_bf16 v[30:33], v[62:65], v[46:49], v[30:33]
	v_mfma_f32_16x16x32_bf16 v[34:37], v[66:69], v[46:49], v[34:37]
	v_mfma_f32_16x16x32_bf16 v[38:41], v[70:73], v[46:49], v[38:41]
	v_mfma_f32_16x16x32_bf16 v[42:45], v[74:77], v[46:49], v[42:45]
	ds_read_b128 v[46:49], v150 offset:4032
	s_waitcnt lgkmcnt(0)
	v_mfma_f32_16x16x32_bf16 v[74:77], v[6:9], v[46:49], v[30:33]
	s_nop 2
	ds_read_b128 v[30:33], v97 offset:8224
	v_mfma_f32_16x16x32_bf16 v[42:45], v[70:73], v[46:49], v[42:45]
	ds_read_b128 v[70:73], v150 offset:4096
	v_mfma_f32_16x16x32_bf16 v[50:53], v[22:25], v[46:49], v[50:53]
	v_mfma_f32_16x16x32_bf16 v[54:57], v[18:21], v[46:49], v[54:57]
	v_mfma_f32_16x16x32_bf16 v[58:61], v[14:17], v[46:49], v[58:61]
	v_mfma_f32_16x16x32_bf16 v[26:29], v[10:13], v[46:49], v[26:29]
	v_mfma_f32_16x16x32_bf16 v[34:37], v[62:65], v[46:49], v[34:37]
	v_mfma_f32_16x16x32_bf16 v[38:41], v[66:69], v[46:49], v[38:41]
	ds_read_b128 v[46:49], v97 offset:8288
	s_waitcnt lgkmcnt(1)
	v_mfma_f32_16x16x32_bf16 v[50:53], v[30:33], v[70:73], v[50:53]
	v_mfma_f32_16x16x32_bf16 v[54:57], v[22:25], v[70:73], v[54:57]
	v_mfma_f32_16x16x32_bf16 v[80:83], v[18:21], v[70:73], v[58:61]
	v_mfma_f32_16x16x32_bf16 v[26:29], v[14:17], v[70:73], v[26:29]
	v_mfma_f32_16x16x32_bf16 v[74:77], v[10:13], v[70:73], v[74:77]
	v_mfma_f32_16x16x32_bf16 v[34:37], v[6:9], v[70:73], v[34:37]
	v_mfma_f32_16x16x32_bf16 v[132:135], v[62:65], v[70:73], v[38:41]
	v_mfma_f32_16x16x32_bf16 v[66:69], v[66:69], v[70:73], v[42:45]
	ds_read_b128 v[70:73], v150 offset:4160
	s_waitcnt lgkmcnt(0)
	v_mfma_f32_16x16x32_bf16 v[62:65], v[62:65], v[70:73], v[66:69]
	s_nop 4
	ds_read_b128 v[66:69], v150 offset:4224
	v_mfma_f32_16x16x32_bf16 v[42:45], v[18:21], v[70:73], v[26:29]
	v_mfma_f32_16x16x32_bf16 v[38:41], v[14:17], v[70:73], v[74:77]
	v_mfma_f32_16x16x32_bf16 v[26:29], v[6:9], v[70:73], v[132:135]
	s_nop 1
	ds_read_b128 v[74:77], v97 offset:8352
	s_waitcnt lgkmcnt(0)
	s_barrier
	v_lshlrev_b32_e32 v134, 1, v96
	v_mov_b32_e32 v135, v131
	v_mfma_f32_16x16x32_bf16 v[58:61], v[46:49], v[70:73], v[50:53]
	v_mfma_f32_16x16x32_bf16 v[50:53], v[22:25], v[70:73], v[80:83]
	v_mfma_f32_16x16x32_bf16 v[22:25], v[22:25], v[66:69], v[42:45]
	s_nop 2
	v_lshl_add_u64 v[42:43], s[2:3], 0, v[134:135]
	v_mfma_f32_16x16x32_bf16 v[18:21], v[18:21], v[66:69], v[38:41]
	s_nop 2
	v_lshl_add_u64 v[38:39], v[98:99], 1, v[42:43]
	v_add_co_u32_e32 v40, vcc, 0x4000, v38
	v_mfma_f32_16x16x32_bf16 v[54:57], v[30:33], v[70:73], v[54:57]
	s_nop 0
	v_addc_co_u32_e32 v41, vcc, 0, v39, vcc
	global_load_dwordx2 v[84:85], v[40:41], off
	v_mfma_f32_16x16x32_bf16 v[34:37], v[10:13], v[70:73], v[34:37]
	v_lshl_add_u64 v[132:133], v[38:39], 0, s[16:17]
	v_mfma_f32_16x16x32_bf16 v[58:61], v[74:77], v[66:69], v[58:61]
	v_mov_b32_e32 v75, 0
	v_mfma_f32_16x16x32_bf16 v[46:49], v[46:49], v[66:69], v[54:57]
	v_mfma_f32_16x16x32_bf16 v[30:33], v[30:33], v[66:69], v[50:53]
	v_mfma_f32_16x16x32_bf16 v[14:17], v[14:17], v[66:69], v[34:37]
	v_mfma_f32_16x16x32_bf16 v[10:13], v[10:13], v[66:69], v[26:29]
	v_mfma_f32_16x16x32_bf16 v[6:9], v[6:9], v[66:69], v[62:65]
	s_mov_b64 s[0:1], exec
	v_readlane_b32 s4, v255, 37
	v_readlane_b32 s5, v255, 38
	s_and_b64 s[4:5], s[0:1], s[4:5]
	s_mov_b64 exec, s[4:5]
	s_cbranch_execz .LBB0_802
	global_load_short_d16_hi v137, v[132:133], off offset:-2

.LBB0_866:
	s_or_b64 exec, exec, s[4:5]
	ds_read_b128 v[14:17], v97 offset:4064
	ds_read_b128 v[18:21], v97 offset:4000
	ds_read_b128 v[46:49], v149
	ds_read_b128 v[42:45], v97 offset:3680
	ds_read_b128 v[74:77], v97 offset:3616
	ds_read_b128 v[26:29], v97 offset:3936
	ds_read_b128 v[30:33], v97 offset:3872
	ds_read_b128 v[34:37], v97 offset:3808
	ds_read_b128 v[38:41], v97 offset:3744
	ds_read_b128 v[22:25], v97 offset:4128
	ds_read_b128 v[78:81], v150
	s_waitcnt lgkmcnt(7)
	v_mfma_f32_16x16x32_bf16 v[82:85], v[42:45], v[46:49], 0
	s_add_i32 s4, s24, 0x1000
	s_mul_hi_i32 s5, s4, 0xc000
	s_mul_i32 s4, s4, 0xc000
	v_mfma_f32_16x16x32_bf16 v[50:53], v[14:17], v[46:49], 0
	s_add_u32 s42, s20, s4
	s_addc_u32 s43, s68, s5
	v_lshlrev_b32_e32 v222, 1, v96
	v_mov_b32_e32 v223, 0
	v_lshl_add_u64 v[222:223], s[42:43], 0, v[222:223]
	v_lshl_add_u64 v[222:223], v[98:99], 1, v[222:223]
	v_lshl_add_u64 v[222:223], v[222:223], 0, s[16:17]
	global_load_dword v224, v[222:223], off
	global_load_dword v224, v[222:223], off offset:64
	global_load_dword v224, v[222:223], off offset:128
	global_load_dword v224, v[222:223], off offset:192
	global_load_dword v224, v[222:223], off offset:256
	global_load_dword v224, v[222:223], off offset:320
	global_load_dword v224, v[222:223], off offset:384
	global_load_dword v224, v[222:223], off offset:448
	v_mov_b32_e32 v135, v131
	v_mfma_f32_16x16x32_bf16 v[54:57], v[18:21], v[46:49], 0
	s_waitcnt lgkmcnt(5)
	v_mfma_f32_16x16x32_bf16 v[58:61], v[26:29], v[46:49], 0
	s_waitcnt lgkmcnt(4)
	v_mfma_f32_16x16x32_bf16 v[62:65], v[30:33], v[46:49], 0
	s_waitcnt lgkmcnt(3)
	v_mfma_f32_16x16x32_bf16 v[66:69], v[34:37], v[46:49], 0
	s_waitcnt lgkmcnt(2)
	v_mfma_f32_16x16x32_bf16 v[70:73], v[38:41], v[46:49], 0
	v_mfma_f32_16x16x32_bf16 v[46:49], v[74:77], v[46:49], 0
	s_waitcnt lgkmcnt(0)
	v_mfma_f32_16x16x32_bf16 v[74:77], v[38:41], v[78:81], v[82:85]
	s_nop 2
	ds_read_b128 v[82:85], v97 offset:4192
	v_mfma_f32_16x16x32_bf16 v[42:45], v[42:45], v[78:81], v[46:49]
	s_nop 2
	ds_read_b128 v[46:49], v150 offset:64
	v_mfma_f32_16x16x32_bf16 v[50:53], v[22:25], v[78:81], v[50:53]
	v_mfma_f32_16x16x32_bf16 v[54:57], v[14:17], v[78:81], v[54:57]
	v_mfma_f32_16x16x32_bf16 v[58:61], v[18:21], v[78:81], v[58:61]
	v_mfma_f32_16x16x32_bf16 v[62:65], v[26:29], v[78:81], v[62:65]
	v_mfma_f32_16x16x32_bf16 v[66:69], v[30:33], v[78:81], v[66:69]
	v_mfma_f32_16x16x32_bf16 v[70:73], v[34:37], v[78:81], v[70:73]
	ds_read_b128 v[78:81], v97 offset:4256
	s_waitcnt lgkmcnt(1)
	v_mfma_f32_16x16x32_bf16 v[38:41], v[38:41], v[46:49], v[42:45]
	s_nop 2
	ds_read_b128 v[42:45], v150 offset:128
	v_mfma_f32_16x16x32_bf16 v[50:53], v[82:85], v[46:49], v[50:53]
	v_mfma_f32_16x16x32_bf16 v[54:57], v[22:25], v[46:49], v[54:57]
	v_mfma_f32_16x16x32_bf16 v[58:61], v[14:17], v[46:49], v[58:61]
	v_mfma_f32_16x16x32_bf16 v[62:65], v[18:21], v[46:49], v[62:65]
	v_mfma_f32_16x16x32_bf16 v[66:69], v[26:29], v[46:49], v[66:69]
	v_mfma_f32_16x16x32_bf16 v[70:73], v[30:33], v[46:49], v[70:73]
	v_mfma_f32_16x16x32_bf16 v[74:77], v[34:37], v[46:49], v[74:77]
	s_waitcnt lgkmcnt(0)
	v_mfma_f32_16x16x32_bf16 v[46:49], v[78:81], v[42:45], v[50:53]
	v_mfma_f32_16x16x32_bf16 v[50:53], v[82:85], v[42:45], v[54:57]
	v_mfma_f32_16x16x32_bf16 v[54:57], v[22:25], v[42:45], v[58:61]
	v_mfma_f32_16x16x32_bf16 v[58:61], v[14:17], v[42:45], v[62:65]
	v_mfma_f32_16x16x32_bf16 v[62:65], v[18:21], v[42:45], v[66:69]
	v_mfma_f32_16x16x32_bf16 v[66:69], v[26:29], v[42:45], v[70:73]
	v_mfma_f32_16x16x32_bf16 v[70:73], v[30:33], v[42:45], v[74:77]
	s_nop 2
	ds_read_b128 v[74:77], v97 offset:4320
	v_mfma_f32_16x16x32_bf16 v[34:37], v[34:37], v[42:45], v[38:41]
	s_nop 2
	ds_read_b128 v[38:41], v150 offset:192
	s_waitcnt lgkmcnt(0)
	v_mfma_f32_16x16x32_bf16 v[42:45], v[74:77], v[38:41], v[46:49]
	v_mfma_f32_16x16x32_bf16 v[46:49], v[78:81], v[38:41], v[50:53]
	v_mfma_f32_16x16x32_bf16 v[50:53], v[82:85], v[38:41], v[54:57]
	v_mfma_f32_16x16x32_bf16 v[54:57], v[22:25], v[38:41], v[58:61]
	v_mfma_f32_16x16x32_bf16 v[58:61], v[14:17], v[38:41], v[62:65]
	v_mfma_f32_16x16x32_bf16 v[62:65], v[18:21], v[38:41], v[66:69]
	v_mfma_f32_16x16x32_bf16 v[66:69], v[26:29], v[38:41], v[70:73]
	s_nop 2
	ds_read_b128 v[70:73], v97 offset:4384
	v_mfma_f32_16x16x32_bf16 v[30:33], v[30:33], v[38:41], v[34:37]
	s_nop 2
	ds_read_b128 v[34:37], v150 offset:256
	s_waitcnt lgkmcnt(0)
	v_mfma_f32_16x16x32_bf16 v[38:41], v[70:73], v[34:37], v[42:45]
	v_mfma_f32_16x16x32_bf16 v[42:45], v[74:77], v[34:37], v[46:49]
	v_mfma_f32_16x16x32_bf16 v[46:49], v[78:81], v[34:37], v[50:53]
	v_mfma_f32_16x16x32_bf16 v[50:53], v[82:85], v[34:37], v[54:57]
	v_mfma_f32_16x16x32_bf16 v[54:57], v[22:25], v[34:37], v[58:61]
	v_mfma_f32_16x16x32_bf16 v[58:61], v[14:17], v[34:37], v[62:65]
	v_mfma_f32_16x16x32_bf16 v[62:65], v[18:21], v[34:37], v[66:69]
	s_nop 2
	ds_read_b128 v[66:69], v97 offset:4448
	v_mfma_f32_16x16x32_bf16 v[26:29], v[26:29], v[34:37], v[30:33]
	s_nop 2
	ds_read_b128 v[30:33], v150 offset:320
	s_waitcnt lgkmcnt(0)
	v_mfma_f32_16x16x32_bf16 v[34:37], v[66:69], v[30:33], v[38:41]
	v_mfma_f32_16x16x32_bf16 v[38:41], v[70:73], v[30:33], v[42:45]
	v_mfma_f32_16x16x32_bf16 v[42:45], v[74:77], v[30:33], v[46:49]
	v_mfma_f32_16x16x32_bf16 v[46:49], v[78:81], v[30:33], v[50:53]
	v_mfma_f32_16x16x32_bf16 v[50:53], v[82:85], v[30:33], v[54:57]
	v_mfma_f32_16x16x32_bf16 v[54:57], v[22:25], v[30:33], v[58:61]
	v_mfma_f32_16x16x32_bf16 v[58:61], v[14:17], v[30:33], v[62:65]
	s_nop 2
	ds_read_b128 v[62:65], v97 offset:4512
	v_mfma_f32_16x16x32_bf16 v[18:21], v[18:21], v[30:33], v[26:29]
	s_nop 2
	ds_read_b128 v[26:29], v150 offset:384
	s_waitcnt lgkmcnt(0)
	v_mfma_f32_16x16x32_bf16 v[30:33], v[62:65], v[26:29], v[34:37]
	v_mfma_f32_16x16x32_bf16 v[34:37], v[66:69], v[26:29], v[38:41]
	v_mfma_f32_16x16x32_bf16 v[38:41], v[70:73], v[26:29], v[42:45]
	v_mfma_f32_16x16x32_bf16 v[42:45], v[74:77], v[26:29], v[46:49]
	v_mfma_f32_16x16x32_bf16 v[46:49], v[78:81], v[26:29], v[50:53]
	v_mfma_f32_16x16x32_bf16 v[50:53], v[82:85], v[26:29], v[54:57]
	v_mfma_f32_16x16x32_bf16 v[54:57], v[22:25], v[26:29], v[58:61]
	s_nop 2
	ds_read_b128 v[58:61], v97 offset:4576
	v_mfma_f32_16x16x32_bf16 v[14:17], v[14:17], v[26:29], v[18:21]
	s_nop 2
	ds_read_b128 v[18:21], v150 offset:448
	s_waitcnt lgkmcnt(0)
	v_mfma_f32_16x16x32_bf16 v[26:29], v[58:61], v[18:21], v[30:33]
	v_mfma_f32_16x16x32_bf16 v[30:33], v[62:65], v[18:21], v[34:37]
	v_mfma_f32_16x16x32_bf16 v[34:37], v[66:69], v[18:21], v[38:41]
	v_mfma_f32_16x16x32_bf16 v[38:41], v[70:73], v[18:21], v[42:45]
	v_mfma_f32_16x16x32_bf16 v[42:45], v[74:77], v[18:21], v[46:49]
	v_mfma_f32_16x16x32_bf16 v[46:49], v[78:81], v[18:21], v[50:53]
	v_mfma_f32_16x16x32_bf16 v[50:53], v[82:85], v[18:21], v[54:57]
	s_nop 2
	ds_read_b128 v[54:57], v97 offset:4640
	v_mfma_f32_16x16x32_bf16 v[14:17], v[22:25], v[18:21], v[14:17]
	ds_read_b128 v[18:21], v150 offset:512
	s_waitcnt lgkmcnt(0)
	v_mfma_f32_16x16x32_bf16 v[14:17], v[82:85], v[18:21], v[14:17]
	ds_read_b128 v[82:85], v97 offset:4768
	v_mfma_f32_16x16x32_bf16 v[22:25], v[54:57], v[18:21], v[26:29]
	v_mfma_f32_16x16x32_bf16 v[26:29], v[58:61], v[18:21], v[30:33]
	v_mfma_f32_16x16x32_bf16 v[30:33], v[62:65], v[18:21], v[34:37]
	v_mfma_f32_16x16x32_bf16 v[34:37], v[66:69], v[18:21], v[38:41]
	v_mfma_f32_16x16x32_bf16 v[38:41], v[70:73], v[18:21], v[42:45]
	v_mfma_f32_16x16x32_bf16 v[42:45], v[74:77], v[18:21], v[46:49]
	v_mfma_f32_16x16x32_bf16 v[46:49], v[78:81], v[18:21], v[50:53]
	ds_read_b128 v[18:21], v150 offset:576
	s_nop 1
	ds_read_b128 v[50:53], v97 offset:4704
	s_waitcnt lgkmcnt(1)
	v_mfma_f32_16x16x32_bf16 v[26:29], v[54:57], v[18:21], v[26:29]
	v_mfma_f32_16x16x32_bf16 v[30:33], v[58:61], v[18:21], v[30:33]
	v_mfma_f32_16x16x32_bf16 v[34:37], v[62:65], v[18:21], v[34:37]
	v_mfma_f32_16x16x32_bf16 v[38:41], v[66:69], v[18:21], v[38:41]
	v_mfma_f32_16x16x32_bf16 v[42:45], v[70:73], v[18:21], v[42:45]
	v_mfma_f32_16x16x32_bf16 v[46:49], v[74:77], v[18:21], v[46:49]
	v_mfma_f32_16x16x32_bf16 v[14:17], v[78:81], v[18:21], v[14:17]
	ds_read_b128 v[78:81], v97 offset:4832
	s_waitcnt lgkmcnt(1)
	v_mfma_f32_16x16x32_bf16 v[22:25], v[50:53], v[18:21], v[22:25]
	ds_read_b128 v[18:21], v150 offset:640
	s_waitcnt lgkmcnt(0)
	v_mfma_f32_16x16x32_bf16 v[22:25], v[82:85], v[18:21], v[22:25]
	v_mfma_f32_16x16x32_bf16 v[26:29], v[50:53], v[18:21], v[26:29]
	v_mfma_f32_16x16x32_bf16 v[30:33], v[54:57], v[18:21], v[30:33]
	v_mfma_f32_16x16x32_bf16 v[34:37], v[58:61], v[18:21], v[34:37]
	v_mfma_f32_16x16x32_bf16 v[38:41], v[62:65], v[18:21], v[38:41]
	v_mfma_f32_16x16x32_bf16 v[42:45], v[66:69], v[18:21], v[42:45]
	v_mfma_f32_16x16x32_bf16 v[46:49], v[70:73], v[18:21], v[46:49]
	v_mfma_f32_16x16x32_bf16 v[14:17], v[74:77], v[18:21], v[14:17]
	ds_read_b128 v[18:21], v150 offset:704
	ds_read_b128 v[74:77], v97 offset:4896
	s_waitcnt lgkmcnt(1)
	v_mfma_f32_16x16x32_bf16 v[22:25], v[78:81], v[18:21], v[22:25]
	v_mfma_f32_16x16x32_bf16 v[26:29], v[82:85], v[18:21], v[26:29]
	v_mfma_f32_16x16x32_bf16 v[30:33], v[50:53], v[18:21], v[30:33]
	v_mfma_f32_16x16x32_bf16 v[34:37], v[54:57], v[18:21], v[34:37]
	v_mfma_f32_16x16x32_bf16 v[38:41], v[58:61], v[18:21], v[38:41]
	v_mfma_f32_16x16x32_bf16 v[42:45], v[62:65], v[18:21], v[42:45]
	v_mfma_f32_16x16x32_bf16 v[46:49], v[66:69], v[18:21], v[46:49]
	v_mfma_f32_16x16x32_bf16 v[14:17], v[70:73], v[18:21], v[14:17]
	ds_read_b128 v[18:21], v150 offset:768
	ds_read_b128 v[70:73], v97 offset:4960
	s_waitcnt lgkmcnt(1)
	v_mfma_f32_16x16x32_bf16 v[22:25], v[74:77], v[18:21], v[22:25]
	v_mfma_f32_16x16x32_bf16 v[26:29], v[78:81], v[18:21], v[26:29]
	v_mfma_f32_16x16x32_bf16 v[30:33], v[82:85], v[18:21], v[30:33]
	v_mfma_f32_16x16x32_bf16 v[34:37], v[50:53], v[18:21], v[34:37]
	v_mfma_f32_16x16x32_bf16 v[38:41], v[54:57], v[18:21], v[38:41]
	v_mfma_f32_16x16x32_bf16 v[42:45], v[58:61], v[18:21], v[42:45]
	v_mfma_f32_16x16x32_bf16 v[46:49], v[62:65], v[18:21], v[46:49]
	v_mfma_f32_16x16x32_bf16 v[14:17], v[66:69], v[18:21], v[14:17]
	ds_read_b128 v[18:21], v150 offset:832
	ds_read_b128 v[66:69], v97 offset:5024
	s_waitcnt lgkmcnt(1)
	v_mfma_f32_16x16x32_bf16 v[22:25], v[70:73], v[18:21], v[22:25]
	v_mfma_f32_16x16x32_bf16 v[26:29], v[74:77], v[18:21], v[26:29]
	v_mfma_f32_16x16x32_bf16 v[30:33], v[78:81], v[18:21], v[30:33]
	v_mfma_f32_16x16x32_bf16 v[34:37], v[82:85], v[18:21], v[34:37]
	v_mfma_f32_16x16x32_bf16 v[38:41], v[50:53], v[18:21], v[38:41]
	v_mfma_f32_16x16x32_bf16 v[42:45], v[54:57], v[18:21], v[42:45]
	v_mfma_f32_16x16x32_bf16 v[46:49], v[58:61], v[18:21], v[46:49]
	v_mfma_f32_16x16x32_bf16 v[14:17], v[62:65], v[18:21], v[14:17]
	ds_read_b128 v[18:21], v150 offset:896
	ds_read_b128 v[62:65], v97 offset:5088
	s_waitcnt lgkmcnt(1)
	v_mfma_f32_16x16x32_bf16 v[22:25], v[66:69], v[18:21], v[22:25]
	v_mfma_f32_16x16x32_bf16 v[26:29], v[70:73], v[18:21], v[26:29]
	v_mfma_f32_16x16x32_bf16 v[30:33], v[74:77], v[18:21], v[30:33]
	v_mfma_f32_16x16x32_bf16 v[34:37], v[78:81], v[18:21], v[34:37]
	v_mfma_f32_16x16x32_bf16 v[38:41], v[82:85], v[18:21], v[38:41]
	v_mfma_f32_16x16x32_bf16 v[42:45], v[50:53], v[18:21], v[42:45]
	v_mfma_f32_16x16x32_bf16 v[46:49], v[54:57], v[18:21], v[46:49]
	v_mfma_f32_16x16x32_bf16 v[14:17], v[58:61], v[18:21], v[14:17]
	ds_read_b128 v[18:21], v150 offset:960
	ds_read_b128 v[58:61], v97 offset:5152
	s_waitcnt lgkmcnt(1)
	v_mfma_f32_16x16x32_bf16 v[22:25], v[62:65], v[18:21], v[22:25]
	v_mfma_f32_16x16x32_bf16 v[26:29], v[66:69], v[18:21], v[26:29]
	v_mfma_f32_16x16x32_bf16 v[30:33], v[70:73], v[18:21], v[30:33]
	v_mfma_f32_16x16x32_bf16 v[34:37], v[74:77], v[18:21], v[34:37]
	v_mfma_f32_16x16x32_bf16 v[38:41], v[78:81], v[18:21], v[38:41]
	v_mfma_f32_16x16x32_bf16 v[42:45], v[82:85], v[18:21], v[42:45]
	v_mfma_f32_16x16x32_bf16 v[46:49], v[50:53], v[18:21], v[46:49]
	v_mfma_f32_16x16x32_bf16 v[14:17], v[54:57], v[18:21], v[14:17]
	ds_read_b128 v[18:21], v150 offset:1024
	ds_read_b128 v[54:57], v97 offset:5216
	s_waitcnt lgkmcnt(1)
	v_mfma_f32_16x16x32_bf16 v[22:25], v[58:61], v[18:21], v[22:25]
	v_mfma_f32_16x16x32_bf16 v[26:29], v[62:65], v[18:21], v[26:29]
	v_mfma_f32_16x16x32_bf16 v[30:33], v[66:69], v[18:21], v[30:33]
	v_mfma_f32_16x16x32_bf16 v[34:37], v[70:73], v[18:21], v[34:37]
	v_mfma_f32_16x16x32_bf16 v[38:41], v[74:77], v[18:21], v[38:41]
	v_mfma_f32_16x16x32_bf16 v[42:45], v[78:81], v[18:21], v[42:45]
	v_mfma_f32_16x16x32_bf16 v[46:49], v[82:85], v[18:21], v[46:49]
	v_mfma_f32_16x16x32_bf16 v[14:17], v[50:53], v[18:21], v[14:17]
	ds_read_b128 v[18:21], v150 offset:1088
	ds_read_b128 v[50:53], v97 offset:5280
	s_waitcnt lgkmcnt(1)
	v_mfma_f32_16x16x32_bf16 v[22:25], v[54:57], v[18:21], v[22:25]
	v_mfma_f32_16x16x32_bf16 v[26:29], v[58:61], v[18:21], v[26:29]
	v_mfma_f32_16x16x32_bf16 v[30:33], v[62:65], v[18:21], v[30:33]
	v_mfma_f32_16x16x32_bf16 v[34:37], v[66:69], v[18:21], v[34:37]
	v_mfma_f32_16x16x32_bf16 v[38:41], v[70:73], v[18:21], v[38:41]
	v_mfma_f32_16x16x32_bf16 v[42:45], v[74:77], v[18:21], v[42:45]
	v_mfma_f32_16x16x32_bf16 v[46:49], v[78:81], v[18:21], v[46:49]
	v_mfma_f32_16x16x32_bf16 v[14:17], v[82:85], v[18:21], v[14:17]
	ds_read_b128 v[18:21], v150 offset:1152
	ds_read_b128 v[82:85], v97 offset:5344
	s_waitcnt lgkmcnt(1)
	v_mfma_f32_16x16x32_bf16 v[22:25], v[50:53], v[18:21], v[22:25]
	v_mfma_f32_16x16x32_bf16 v[26:29], v[54:57], v[18:21], v[26:29]
	v_mfma_f32_16x16x32_bf16 v[30:33], v[58:61], v[18:21], v[30:33]
	v_mfma_f32_16x16x32_bf16 v[34:37], v[62:65], v[18:21], v[34:37]
	v_mfma_f32_16x16x32_bf16 v[38:41], v[66:69], v[18:21], v[38:41]
	v_mfma_f32_16x16x32_bf16 v[42:45], v[70:73], v[18:21], v[42:45]
	v_mfma_f32_16x16x32_bf16 v[46:49], v[74:77], v[18:21], v[46:49]
	v_mfma_f32_16x16x32_bf16 v[14:17], v[78:81], v[18:21], v[14:17]
	ds_read_b128 v[18:21], v150 offset:1216
	ds_read_b128 v[78:81], v97 offset:5408
	s_waitcnt lgkmcnt(1)
	v_mfma_f32_16x16x32_bf16 v[22:25], v[82:85], v[18:21], v[22:25]
	v_mfma_f32_16x16x32_bf16 v[26:29], v[50:53], v[18:21], v[26:29]
	v_mfma_f32_16x16x32_bf16 v[30:33], v[54:57], v[18:21], v[30:33]
	v_mfma_f32_16x16x32_bf16 v[34:37], v[58:61], v[18:21], v[34:37]
	v_mfma_f32_16x16x32_bf16 v[38:41], v[62:65], v[18:21], v[38:41]
	v_mfma_f32_16x16x32_bf16 v[42:45], v[66:69], v[18:21], v[42:45]
	v_mfma_f32_16x16x32_bf16 v[46:49], v[70:73], v[18:21], v[46:49]
	v_mfma_f32_16x16x32_bf16 v[14:17], v[74:77], v[18:21], v[14:17]
	ds_read_b128 v[18:21], v150 offset:1280
	ds_read_b128 v[74:77], v97 offset:5472
	s_waitcnt lgkmcnt(1)
	v_mfma_f32_16x16x32_bf16 v[22:25], v[78:81], v[18:21], v[22:25]
	v_mfma_f32_16x16x32_bf16 v[26:29], v[82:85], v[18:21], v[26:29]
	v_mfma_f32_16x16x32_bf16 v[30:33], v[50:53], v[18:21], v[30:33]
	v_mfma_f32_16x16x32_bf16 v[34:37], v[54:57], v[18:21], v[34:37]
	v_mfma_f32_16x16x32_bf16 v[38:41], v[58:61], v[18:21], v[38:41]
	v_mfma_f32_16x16x32_bf16 v[42:45], v[62:65], v[18:21], v[42:45]
	v_mfma_f32_16x16x32_bf16 v[46:49], v[66:69], v[18:21], v[46:49]
	v_mfma_f32_16x16x32_bf16 v[14:17], v[70:73], v[18:21], v[14:17]
	ds_read_b128 v[18:21], v150 offset:1344
	ds_read_b128 v[70:73], v97 offset:5536
	s_waitcnt lgkmcnt(1)
	v_mfma_f32_16x16x32_bf16 v[22:25], v[74:77], v[18:21], v[22:25]
	v_mfma_f32_16x16x32_bf16 v[26:29], v[78:81], v[18:21], v[26:29]
	v_mfma_f32_16x16x32_bf16 v[30:33], v[82:85], v[18:21], v[30:33]
	v_mfma_f32_16x16x32_bf16 v[34:37], v[50:53], v[18:21], v[34:37]
	v_mfma_f32_16x16x32_bf16 v[38:41], v[54:57], v[18:21], v[38:41]
	v_mfma_f32_16x16x32_bf16 v[42:45], v[58:61], v[18:21], v[42:45]
	v_mfma_f32_16x16x32_bf16 v[46:49], v[62:65], v[18:21], v[46:49]
	v_mfma_f32_16x16x32_bf16 v[14:17], v[66:69], v[18:21], v[14:17]
	ds_read_b128 v[18:21], v150 offset:1408
	ds_read_b128 v[66:69], v97 offset:5600
	s_waitcnt lgkmcnt(1)
	v_mfma_f32_16x16x32_bf16 v[22:25], v[70:73], v[18:21], v[22:25]
	v_mfma_f32_16x16x32_bf16 v[26:29], v[74:77], v[18:21], v[26:29]
	v_mfma_f32_16x16x32_bf16 v[30:33], v[78:81], v[18:21], v[30:33]
	v_mfma_f32_16x16x32_bf16 v[34:37], v[82:85], v[18:21], v[34:37]
	v_mfma_f32_16x16x32_bf16 v[38:41], v[50:53], v[18:21], v[38:41]
	v_mfma_f32_16x16x32_bf16 v[42:45], v[54:57], v[18:21], v[42:45]
	v_mfma_f32_16x16x32_bf16 v[46:49], v[58:61], v[18:21], v[46:49]
	v_mfma_f32_16x16x32_bf16 v[14:17], v[62:65], v[18:21], v[14:17]
	ds_read_b128 v[18:21], v150 offset:1472
	ds_read_b128 v[62:65], v97 offset:5664
	s_waitcnt lgkmcnt(1)
	v_mfma_f32_16x16x32_bf16 v[22:25], v[66:69], v[18:21], v[22:25]
	v_mfma_f32_16x16x32_bf16 v[26:29], v[70:73], v[18:21], v[26:29]
	v_mfma_f32_16x16x32_bf16 v[30:33], v[74:77], v[18:21], v[30:33]
	v_mfma_f32_16x16x32_bf16 v[34:37], v[78:81], v[18:21], v[34:37]
	v_mfma_f32_16x16x32_bf16 v[38:41], v[82:85], v[18:21], v[38:41]
	v_mfma_f32_16x16x32_bf16 v[42:45], v[50:53], v[18:21], v[42:45]
	v_mfma_f32_16x16x32_bf16 v[46:49], v[54:57], v[18:21], v[46:49]
	v_mfma_f32_16x16x32_bf16 v[14:17], v[58:61], v[18:21], v[14:17]
	ds_read_b128 v[18:21], v150 offset:1536
	ds_read_b128 v[58:61], v97 offset:5728
	s_waitcnt lgkmcnt(1)
	v_mfma_f32_16x16x32_bf16 v[22:25], v[62:65], v[18:21], v[22:25]
	v_mfma_f32_16x16x32_bf16 v[26:29], v[66:69], v[18:21], v[26:29]
	v_mfma_f32_16x16x32_bf16 v[30:33], v[70:73], v[18:21], v[30:33]
	v_mfma_f32_16x16x32_bf16 v[34:37], v[74:77], v[18:21], v[34:37]
	v_mfma_f32_16x16x32_bf16 v[38:41], v[78:81], v[18:21], v[38:41]
	v_mfma_f32_16x16x32_bf16 v[42:45], v[82:85], v[18:21], v[42:45]
	v_mfma_f32_16x16x32_bf16 v[46:49], v[50:53], v[18:21], v[46:49]
	v_mfma_f32_16x16x32_bf16 v[14:17], v[54:57], v[18:21], v[14:17]
	ds_read_b128 v[18:21], v150 offset:1600
	ds_read_b128 v[54:57], v97 offset:5792
	s_waitcnt lgkmcnt(1)
	v_mfma_f32_16x16x32_bf16 v[22:25], v[58:61], v[18:21], v[22:25]
	v_mfma_f32_16x16x32_bf16 v[26:29], v[62:65], v[18:21], v[26:29]
	v_mfma_f32_16x16x32_bf16 v[30:33], v[66:69], v[18:21], v[30:33]
	v_mfma_f32_16x16x32_bf16 v[34:37], v[70:73], v[18:21], v[34:37]
	v_mfma_f32_16x16x32_bf16 v[38:41], v[74:77], v[18:21], v[38:41]
	v_mfma_f32_16x16x32_bf16 v[42:45], v[78:81], v[18:21], v[42:45]
	v_mfma_f32_16x16x32_bf16 v[46:49], v[82:85], v[18:21], v[46:49]
	v_mfma_f32_16x16x32_bf16 v[14:17], v[50:53], v[18:21], v[14:17]
	ds_read_b128 v[18:21], v150 offset:1664
	ds_read_b128 v[50:53], v97 offset:5856
	s_waitcnt lgkmcnt(1)
	v_mfma_f32_16x16x32_bf16 v[22:25], v[54:57], v[18:21], v[22:25]
	v_mfma_f32_16x16x32_bf16 v[26:29], v[58:61], v[18:21], v[26:29]
	v_mfma_f32_16x16x32_bf16 v[30:33], v[62:65], v[18:21], v[30:33]
	v_mfma_f32_16x16x32_bf16 v[34:37], v[66:69], v[18:21], v[34:37]
	v_mfma_f32_16x16x32_bf16 v[38:41], v[70:73], v[18:21], v[38:41]
	v_mfma_f32_16x16x32_bf16 v[42:45], v[74:77], v[18:21], v[42:45]
	v_mfma_f32_16x16x32_bf16 v[46:49], v[78:81], v[18:21], v[46:49]
	v_mfma_f32_16x16x32_bf16 v[14:17], v[82:85], v[18:21], v[14:17]
	ds_read_b128 v[18:21], v150 offset:1728
	ds_read_b128 v[82:85], v97 offset:5920
	s_waitcnt lgkmcnt(1)
	v_mfma_f32_16x16x32_bf16 v[22:25], v[50:53], v[18:21], v[22:25]
	v_mfma_f32_16x16x32_bf16 v[26:29], v[54:57], v[18:21], v[26:29]
	v_mfma_f32_16x16x32_bf16 v[30:33], v[58:61], v[18:21], v[30:33]
	v_mfma_f32_16x16x32_bf16 v[34:37], v[62:65], v[18:21], v[34:37]
	v_mfma_f32_16x16x32_bf16 v[38:41], v[66:69], v[18:21], v[38:41]
	v_mfma_f32_16x16x32_bf16 v[42:45], v[70:73], v[18:21], v[42:45]
	v_mfma_f32_16x16x32_bf16 v[46:49], v[74:77], v[18:21], v[46:49]
	v_mfma_f32_16x16x32_bf16 v[14:17], v[78:81], v[18:21], v[14:17]
	ds_read_b128 v[18:21], v150 offset:1792
	ds_read_b128 v[78:81], v97 offset:5984
	s_waitcnt lgkmcnt(1)
	v_mfma_f32_16x16x32_bf16 v[22:25], v[82:85], v[18:21], v[22:25]
	v_mfma_f32_16x16x32_bf16 v[26:29], v[50:53], v[18:21], v[26:29]
	v_mfma_f32_16x16x32_bf16 v[30:33], v[54:57], v[18:21], v[30:33]
	v_mfma_f32_16x16x32_bf16 v[34:37], v[58:61], v[18:21], v[34:37]
	v_mfma_f32_16x16x32_bf16 v[38:41], v[62:65], v[18:21], v[38:41]
	v_mfma_f32_16x16x32_bf16 v[42:45], v[66:69], v[18:21], v[42:45]
	v_mfma_f32_16x16x32_bf16 v[46:49], v[70:73], v[18:21], v[46:49]
	v_mfma_f32_16x16x32_bf16 v[14:17], v[74:77], v[18:21], v[14:17]
	ds_read_b128 v[18:21], v150 offset:1856
	ds_read_b128 v[74:77], v97 offset:6048
	s_waitcnt lgkmcnt(1)
	v_mfma_f32_16x16x32_bf16 v[22:25], v[78:81], v[18:21], v[22:25]
	v_mfma_f32_16x16x32_bf16 v[26:29], v[82:85], v[18:21], v[26:29]
	v_mfma_f32_16x16x32_bf16 v[30:33], v[50:53], v[18:21], v[30:33]
	v_mfma_f32_16x16x32_bf16 v[34:37], v[54:57], v[18:21], v[34:37]
	v_mfma_f32_16x16x32_bf16 v[38:41], v[58:61], v[18:21], v[38:41]
	v_mfma_f32_16x16x32_bf16 v[42:45], v[62:65], v[18:21], v[42:45]
	v_mfma_f32_16x16x32_bf16 v[46:49], v[66:69], v[18:21], v[46:49]
	v_mfma_f32_16x16x32_bf16 v[14:17], v[70:73], v[18:21], v[14:17]
	ds_read_b128 v[18:21], v150 offset:1920
	ds_read_b128 v[70:73], v97 offset:6112
	s_waitcnt lgkmcnt(1)
	v_mfma_f32_16x16x32_bf16 v[22:25], v[74:77], v[18:21], v[22:25]
	v_mfma_f32_16x16x32_bf16 v[26:29], v[78:81], v[18:21], v[26:29]
	v_mfma_f32_16x16x32_bf16 v[30:33], v[82:85], v[18:21], v[30:33]
	v_mfma_f32_16x16x32_bf16 v[34:37], v[50:53], v[18:21], v[34:37]
	v_mfma_f32_16x16x32_bf16 v[38:41], v[54:57], v[18:21], v[38:41]
	v_mfma_f32_16x16x32_bf16 v[42:45], v[58:61], v[18:21], v[42:45]
	v_mfma_f32_16x16x32_bf16 v[46:49], v[62:65], v[18:21], v[46:49]
	v_mfma_f32_16x16x32_bf16 v[14:17], v[66:69], v[18:21], v[14:17]
	ds_read_b128 v[18:21], v150 offset:1984
	ds_read_b128 v[66:69], v97 offset:6176
	s_waitcnt lgkmcnt(1)
	v_mfma_f32_16x16x32_bf16 v[22:25], v[70:73], v[18:21], v[22:25]
	v_mfma_f32_16x16x32_bf16 v[26:29], v[74:77], v[18:21], v[26:29]
	v_mfma_f32_16x16x32_bf16 v[30:33], v[78:81], v[18:21], v[30:33]
	v_mfma_f32_16x16x32_bf16 v[34:37], v[82:85], v[18:21], v[34:37]
	v_mfma_f32_16x16x32_bf16 v[38:41], v[50:53], v[18:21], v[38:41]
	v_mfma_f32_16x16x32_bf16 v[42:45], v[54:57], v[18:21], v[42:45]
	v_mfma_f32_16x16x32_bf16 v[46:49], v[58:61], v[18:21], v[46:49]
	v_mfma_f32_16x16x32_bf16 v[14:17], v[62:65], v[18:21], v[14:17]
	ds_read_b128 v[18:21], v150 offset:2048
	ds_read_b128 v[62:65], v97 offset:6240
	s_waitcnt lgkmcnt(1)
	v_mfma_f32_16x16x32_bf16 v[22:25], v[66:69], v[18:21], v[22:25]
	v_mfma_f32_16x16x32_bf16 v[26:29], v[70:73], v[18:21], v[26:29]
	v_mfma_f32_16x16x32_bf16 v[30:33], v[74:77], v[18:21], v[30:33]
	v_mfma_f32_16x16x32_bf16 v[34:37], v[78:81], v[18:21], v[34:37]
	v_mfma_f32_16x16x32_bf16 v[38:41], v[82:85], v[18:21], v[38:41]
	v_mfma_f32_16x16x32_bf16 v[42:45], v[50:53], v[18:21], v[42:45]
	v_mfma_f32_16x16x32_bf16 v[46:49], v[54:57], v[18:21], v[46:49]
	v_mfma_f32_16x16x32_bf16 v[14:17], v[58:61], v[18:21], v[14:17]
	ds_read_b128 v[18:21], v150 offset:2112
	ds_read_b128 v[58:61], v97 offset:6304
	s_waitcnt lgkmcnt(1)
	v_mfma_f32_16x16x32_bf16 v[22:25], v[62:65], v[18:21], v[22:25]
	v_mfma_f32_16x16x32_bf16 v[26:29], v[66:69], v[18:21], v[26:29]
	v_mfma_f32_16x16x32_bf16 v[30:33], v[70:73], v[18:21], v[30:33]
	v_mfma_f32_16x16x32_bf16 v[34:37], v[74:77], v[18:21], v[34:37]
	v_mfma_f32_16x16x32_bf16 v[38:41], v[78:81], v[18:21], v[38:41]
	v_mfma_f32_16x16x32_bf16 v[42:45], v[82:85], v[18:21], v[42:45]
	v_mfma_f32_16x16x32_bf16 v[46:49], v[50:53], v[18:21], v[46:49]
	v_mfma_f32_16x16x32_bf16 v[14:17], v[54:57], v[18:21], v[14:17]
	ds_read_b128 v[18:21], v150 offset:2176
	ds_read_b128 v[54:57], v97 offset:6368
	s_waitcnt lgkmcnt(1)
	v_mfma_f32_16x16x32_bf16 v[22:25], v[58:61], v[18:21], v[22:25]
	v_mfma_f32_16x16x32_bf16 v[26:29], v[62:65], v[18:21], v[26:29]
	v_mfma_f32_16x16x32_bf16 v[30:33], v[66:69], v[18:21], v[30:33]
	v_mfma_f32_16x16x32_bf16 v[34:37], v[70:73], v[18:21], v[34:37]
	v_mfma_f32_16x16x32_bf16 v[38:41], v[74:77], v[18:21], v[38:41]
	v_mfma_f32_16x16x32_bf16 v[42:45], v[78:81], v[18:21], v[42:45]
	v_mfma_f32_16x16x32_bf16 v[46:49], v[82:85], v[18:21], v[46:49]
	v_mfma_f32_16x16x32_bf16 v[14:17], v[50:53], v[18:21], v[14:17]
	ds_read_b128 v[18:21], v150 offset:2240
	ds_read_b128 v[50:53], v97 offset:6432
	s_waitcnt lgkmcnt(1)
	v_mfma_f32_16x16x32_bf16 v[22:25], v[54:57], v[18:21], v[22:25]
	v_mfma_f32_16x16x32_bf16 v[26:29], v[58:61], v[18:21], v[26:29]
	v_mfma_f32_16x16x32_bf16 v[30:33], v[62:65], v[18:21], v[30:33]
	v_mfma_f32_16x16x32_bf16 v[34:37], v[66:69], v[18:21], v[34:37]
	v_mfma_f32_16x16x32_bf16 v[38:41], v[70:73], v[18:21], v[38:41]
	v_mfma_f32_16x16x32_bf16 v[42:45], v[74:77], v[18:21], v[42:45]
	v_mfma_f32_16x16x32_bf16 v[46:49], v[78:81], v[18:21], v[46:49]
	v_mfma_f32_16x16x32_bf16 v[14:17], v[82:85], v[18:21], v[14:17]
	ds_read_b128 v[18:21], v150 offset:2304
	ds_read_b128 v[82:85], v97 offset:6496
	s_waitcnt lgkmcnt(1)
	v_mfma_f32_16x16x32_bf16 v[22:25], v[50:53], v[18:21], v[22:25]
	v_mfma_f32_16x16x32_bf16 v[26:29], v[54:57], v[18:21], v[26:29]
	v_mfma_f32_16x16x32_bf16 v[30:33], v[58:61], v[18:21], v[30:33]
	v_mfma_f32_16x16x32_bf16 v[34:37], v[62:65], v[18:21], v[34:37]
	v_mfma_f32_16x16x32_bf16 v[38:41], v[66:69], v[18:21], v[38:41]
	v_mfma_f32_16x16x32_bf16 v[42:45], v[70:73], v[18:21], v[42:45]
	v_mfma_f32_16x16x32_bf16 v[46:49], v[74:77], v[18:21], v[46:49]
	v_mfma_f32_16x16x32_bf16 v[14:17], v[78:81], v[18:21], v[14:17]
	ds_read_b128 v[18:21], v150 offset:2368
	ds_read_b128 v[78:81], v97 offset:6560
	s_waitcnt lgkmcnt(1)
	v_mfma_f32_16x16x32_bf16 v[22:25], v[82:85], v[18:21], v[22:25]
	v_mfma_f32_16x16x32_bf16 v[26:29], v[50:53], v[18:21], v[26:29]
	v_mfma_f32_16x16x32_bf16 v[30:33], v[54:57], v[18:21], v[30:33]
	v_mfma_f32_16x16x32_bf16 v[34:37], v[58:61], v[18:21], v[34:37]
	v_mfma_f32_16x16x32_bf16 v[38:41], v[62:65], v[18:21], v[38:41]
	v_mfma_f32_16x16x32_bf16 v[42:45], v[66:69], v[18:21], v[42:45]
	v_mfma_f32_16x16x32_bf16 v[46:49], v[70:73], v[18:21], v[46:49]
	v_mfma_f32_16x16x32_bf16 v[14:17], v[74:77], v[18:21], v[14:17]
	ds_read_b128 v[18:21], v150 offset:2432
	ds_read_b128 v[74:77], v97 offset:6624
	s_waitcnt lgkmcnt(1)
	v_mfma_f32_16x16x32_bf16 v[22:25], v[78:81], v[18:21], v[22:25]
	v_mfma_f32_16x16x32_bf16 v[26:29], v[82:85], v[18:21], v[26:29]
	v_mfma_f32_16x16x32_bf16 v[30:33], v[50:53], v[18:21], v[30:33]
	v_mfma_f32_16x16x32_bf16 v[34:37], v[54:57], v[18:21], v[34:37]
	v_mfma_f32_16x16x32_bf16 v[38:41], v[58:61], v[18:21], v[38:41]
	v_mfma_f32_16x16x32_bf16 v[42:45], v[62:65], v[18:21], v[42:45]
	v_mfma_f32_16x16x32_bf16 v[46:49], v[66:69], v[18:21], v[46:49]
	v_mfma_f32_16x16x32_bf16 v[14:17], v[70:73], v[18:21], v[14:17]
	ds_read_b128 v[18:21], v150 offset:2496
	ds_read_b128 v[70:73], v97 offset:6688
	s_waitcnt lgkmcnt(1)
	v_mfma_f32_16x16x32_bf16 v[22:25], v[74:77], v[18:21], v[22:25]
	v_mfma_f32_16x16x32_bf16 v[26:29], v[78:81], v[18:21], v[26:29]
	v_mfma_f32_16x16x32_bf16 v[30:33], v[82:85], v[18:21], v[30:33]
	v_mfma_f32_16x16x32_bf16 v[34:37], v[50:53], v[18:21], v[34:37]
	v_mfma_f32_16x16x32_bf16 v[38:41], v[54:57], v[18:21], v[38:41]
	v_mfma_f32_16x16x32_bf16 v[42:45], v[58:61], v[18:21], v[42:45]
	v_mfma_f32_16x16x32_bf16 v[46:49], v[62:65], v[18:21], v[46:49]
	v_mfma_f32_16x16x32_bf16 v[14:17], v[66:69], v[18:21], v[14:17]
	ds_read_b128 v[18:21], v150 offset:2560
	ds_read_b128 v[66:69], v97 offset:6752
	s_waitcnt lgkmcnt(1)
	v_mfma_f32_16x16x32_bf16 v[22:25], v[70:73], v[18:21], v[22:25]
	v_mfma_f32_16x16x32_bf16 v[26:29], v[74:77], v[18:21], v[26:29]
	v_mfma_f32_16x16x32_bf16 v[30:33], v[78:81], v[18:21], v[30:33]
	v_mfma_f32_16x16x32_bf16 v[34:37], v[82:85], v[18:21], v[34:37]
	v_mfma_f32_16x16x32_bf16 v[38:41], v[50:53], v[18:21], v[38:41]
	v_mfma_f32_16x16x32_bf16 v[42:45], v[54:57], v[18:21], v[42:45]
	v_mfma_f32_16x16x32_bf16 v[46:49], v[58:61], v[18:21], v[46:49]
	v_mfma_f32_16x16x32_bf16 v[14:17], v[62:65], v[18:21], v[14:17]
	ds_read_b128 v[18:21], v150 offset:2624
	ds_read_b128 v[62:65], v97 offset:6816
	s_waitcnt lgkmcnt(1)
	v_mfma_f32_16x16x32_bf16 v[22:25], v[66:69], v[18:21], v[22:25]
	v_mfma_f32_16x16x32_bf16 v[26:29], v[70:73], v[18:21], v[26:29]
	v_mfma_f32_16x16x32_bf16 v[30:33], v[74:77], v[18:21], v[30:33]
	v_mfma_f32_16x16x32_bf16 v[34:37], v[78:81], v[18:21], v[34:37]
	v_mfma_f32_16x16x32_bf16 v[38:41], v[82:85], v[18:21], v[38:41]
	v_mfma_f32_16x16x32_bf16 v[42:45], v[50:53], v[18:21], v[42:45]
	v_mfma_f32_16x16x32_bf16 v[46:49], v[54:57], v[18:21], v[46:49]
	v_mfma_f32_16x16x32_bf16 v[14:17], v[58:61], v[18:21], v[14:17]
	ds_read_b128 v[18:21], v150 offset:2688
	ds_read_b128 v[58:61], v97 offset:6880
	s_waitcnt lgkmcnt(1)
	v_mfma_f32_16x16x32_bf16 v[22:25], v[62:65], v[18:21], v[22:25]
	v_mfma_f32_16x16x32_bf16 v[26:29], v[66:69], v[18:21], v[26:29]
	v_mfma_f32_16x16x32_bf16 v[30:33], v[70:73], v[18:21], v[30:33]
	v_mfma_f32_16x16x32_bf16 v[34:37], v[74:77], v[18:21], v[34:37]
	v_mfma_f32_16x16x32_bf16 v[38:41], v[78:81], v[18:21], v[38:41]
	v_mfma_f32_16x16x32_bf16 v[42:45], v[82:85], v[18:21], v[42:45]
	v_mfma_f32_16x16x32_bf16 v[46:49], v[50:53], v[18:21], v[46:49]
	v_mfma_f32_16x16x32_bf16 v[14:17], v[54:57], v[18:21], v[14:17]
	ds_read_b128 v[18:21], v150 offset:2752
	ds_read_b128 v[54:57], v97 offset:6944
	s_waitcnt lgkmcnt(1)
	v_mfma_f32_16x16x32_bf16 v[22:25], v[58:61], v[18:21], v[22:25]
	v_mfma_f32_16x16x32_bf16 v[26:29], v[62:65], v[18:21], v[26:29]
	v_mfma_f32_16x16x32_bf16 v[30:33], v[66:69], v[18:21], v[30:33]
	v_mfma_f32_16x16x32_bf16 v[34:37], v[70:73], v[18:21], v[34:37]
	v_mfma_f32_16x16x32_bf16 v[38:41], v[74:77], v[18:21], v[38:41]
	v_mfma_f32_16x16x32_bf16 v[42:45], v[78:81], v[18:21], v[42:45]
	v_mfma_f32_16x16x32_bf16 v[46:49], v[82:85], v[18:21], v[46:49]
	v_mfma_f32_16x16x32_bf16 v[14:17], v[50:53], v[18:21], v[14:17]
	ds_read_b128 v[18:21], v150 offset:2816
	ds_read_b128 v[50:53], v97 offset:7008
	s_waitcnt lgkmcnt(1)
	v_mfma_f32_16x16x32_bf16 v[22:25], v[54:57], v[18:21], v[22:25]
	v_mfma_f32_16x16x32_bf16 v[26:29], v[58:61], v[18:21], v[26:29]
	v_mfma_f32_16x16x32_bf16 v[30:33], v[62:65], v[18:21], v[30:33]
	v_mfma_f32_16x16x32_bf16 v[34:37], v[66:69], v[18:21], v[34:37]
	v_mfma_f32_16x16x32_bf16 v[38:41], v[70:73], v[18:21], v[38:41]
	v_mfma_f32_16x16x32_bf16 v[42:45], v[74:77], v[18:21], v[42:45]
	v_mfma_f32_16x16x32_bf16 v[46:49], v[78:81], v[18:21], v[46:49]
	v_mfma_f32_16x16x32_bf16 v[14:17], v[82:85], v[18:21], v[14:17]
	ds_read_b128 v[18:21], v150 offset:2880
	ds_read_b128 v[82:85], v97 offset:7072
	s_waitcnt lgkmcnt(1)
	v_mfma_f32_16x16x32_bf16 v[22:25], v[50:53], v[18:21], v[22:25]
	v_mfma_f32_16x16x32_bf16 v[26:29], v[54:57], v[18:21], v[26:29]
	v_mfma_f32_16x16x32_bf16 v[30:33], v[58:61], v[18:21], v[30:33]
	v_mfma_f32_16x16x32_bf16 v[34:37], v[62:65], v[18:21], v[34:37]
	v_mfma_f32_16x16x32_bf16 v[38:41], v[66:69], v[18:21], v[38:41]
	v_mfma_f32_16x16x32_bf16 v[42:45], v[70:73], v[18:21], v[42:45]
	v_mfma_f32_16x16x32_bf16 v[46:49], v[74:77], v[18:21], v[46:49]
	v_mfma_f32_16x16x32_bf16 v[14:17], v[78:81], v[18:21], v[14:17]
	ds_read_b128 v[18:21], v150 offset:2944
	ds_read_b128 v[78:81], v97 offset:7136
	s_waitcnt lgkmcnt(1)
	v_mfma_f32_16x16x32_bf16 v[22:25], v[82:85], v[18:21], v[22:25]
	v_mfma_f32_16x16x32_bf16 v[26:29], v[50:53], v[18:21], v[26:29]
	v_mfma_f32_16x16x32_bf16 v[30:33], v[54:57], v[18:21], v[30:33]
	v_mfma_f32_16x16x32_bf16 v[34:37], v[58:61], v[18:21], v[34:37]
	v_mfma_f32_16x16x32_bf16 v[38:41], v[62:65], v[18:21], v[38:41]
	v_mfma_f32_16x16x32_bf16 v[42:45], v[66:69], v[18:21], v[42:45]
	v_mfma_f32_16x16x32_bf16 v[46:49], v[70:73], v[18:21], v[46:49]
	v_mfma_f32_16x16x32_bf16 v[14:17], v[74:77], v[18:21], v[14:17]
	ds_read_b128 v[18:21], v150 offset:3008
	ds_read_b128 v[74:77], v97 offset:7200
	s_waitcnt lgkmcnt(1)
	v_mfma_f32_16x16x32_bf16 v[22:25], v[78:81], v[18:21], v[22:25]
	v_mfma_f32_16x16x32_bf16 v[26:29], v[82:85], v[18:21], v[26:29]
	v_mfma_f32_16x16x32_bf16 v[30:33], v[50:53], v[18:21], v[30:33]
	v_mfma_f32_16x16x32_bf16 v[34:37], v[54:57], v[18:21], v[34:37]
	v_mfma_f32_16x16x32_bf16 v[38:41], v[58:61], v[18:21], v[38:41]
	v_mfma_f32_16x16x32_bf16 v[42:45], v[62:65], v[18:21], v[42:45]
	v_mfma_f32_16x16x32_bf16 v[46:49], v[66:69], v[18:21], v[46:49]
	v_mfma_f32_16x16x32_bf16 v[14:17], v[70:73], v[18:21], v[14:17]
	ds_read_b128 v[18:21], v150 offset:3072
	ds_read_b128 v[70:73], v97 offset:7264
	s_waitcnt lgkmcnt(1)
	v_mfma_f32_16x16x32_bf16 v[22:25], v[74:77], v[18:21], v[22:25]
	v_mfma_f32_16x16x32_bf16 v[26:29], v[78:81], v[18:21], v[26:29]
	v_mfma_f32_16x16x32_bf16 v[30:33], v[82:85], v[18:21], v[30:33]
	v_mfma_f32_16x16x32_bf16 v[34:37], v[50:53], v[18:21], v[34:37]
	v_mfma_f32_16x16x32_bf16 v[38:41], v[54:57], v[18:21], v[38:41]
	v_mfma_f32_16x16x32_bf16 v[42:45], v[58:61], v[18:21], v[42:45]
	v_mfma_f32_16x16x32_bf16 v[46:49], v[62:65], v[18:21], v[46:49]
	v_mfma_f32_16x16x32_bf16 v[14:17], v[66:69], v[18:21], v[14:17]
	ds_read_b128 v[18:21], v150 offset:3136
	ds_read_b128 v[66:69], v97 offset:7328
	s_waitcnt lgkmcnt(1)
	v_mfma_f32_16x16x32_bf16 v[22:25], v[70:73], v[18:21], v[22:25]
	v_mfma_f32_16x16x32_bf16 v[26:29], v[74:77], v[18:21], v[26:29]
	v_mfma_f32_16x16x32_bf16 v[30:33], v[78:81], v[18:21], v[30:33]
	v_mfma_f32_16x16x32_bf16 v[34:37], v[82:85], v[18:21], v[34:37]
	v_mfma_f32_16x16x32_bf16 v[38:41], v[50:53], v[18:21], v[38:41]
	v_mfma_f32_16x16x32_bf16 v[42:45], v[54:57], v[18:21], v[42:45]
	v_mfma_f32_16x16x32_bf16 v[46:49], v[58:61], v[18:21], v[46:49]
	v_mfma_f32_16x16x32_bf16 v[14:17], v[62:65], v[18:21], v[14:17]
	ds_read_b128 v[18:21], v150 offset:3200
	ds_read_b128 v[62:65], v97 offset:7392
	s_waitcnt lgkmcnt(1)
	v_mfma_f32_16x16x32_bf16 v[22:25], v[66:69], v[18:21], v[22:25]
	v_mfma_f32_16x16x32_bf16 v[26:29], v[70:73], v[18:21], v[26:29]
	v_mfma_f32_16x16x32_bf16 v[30:33], v[74:77], v[18:21], v[30:33]
	v_mfma_f32_16x16x32_bf16 v[34:37], v[78:81], v[18:21], v[34:37]
	v_mfma_f32_16x16x32_bf16 v[38:41], v[82:85], v[18:21], v[38:41]
	v_mfma_f32_16x16x32_bf16 v[42:45], v[50:53], v[18:21], v[42:45]
	v_mfma_f32_16x16x32_bf16 v[46:49], v[54:57], v[18:21], v[46:49]
	v_mfma_f32_16x16x32_bf16 v[14:17], v[58:61], v[18:21], v[14:17]
	ds_read_b128 v[18:21], v150 offset:3264
	ds_read_b128 v[58:61], v97 offset:7456
	s_waitcnt lgkmcnt(1)
	v_mfma_f32_16x16x32_bf16 v[22:25], v[62:65], v[18:21], v[22:25]
	v_mfma_f32_16x16x32_bf16 v[26:29], v[66:69], v[18:21], v[26:29]
	v_mfma_f32_16x16x32_bf16 v[30:33], v[70:73], v[18:21], v[30:33]
	v_mfma_f32_16x16x32_bf16 v[34:37], v[74:77], v[18:21], v[34:37]
	v_mfma_f32_16x16x32_bf16 v[38:41], v[78:81], v[18:21], v[38:41]
	v_mfma_f32_16x16x32_bf16 v[42:45], v[82:85], v[18:21], v[42:45]
	v_mfma_f32_16x16x32_bf16 v[46:49], v[50:53], v[18:21], v[46:49]
	v_mfma_f32_16x16x32_bf16 v[14:17], v[54:57], v[18:21], v[14:17]
	ds_read_b128 v[18:21], v150 offset:3328
	ds_read_b128 v[54:57], v97 offset:7520
	s_waitcnt lgkmcnt(1)
	v_mfma_f32_16x16x32_bf16 v[22:25], v[58:61], v[18:21], v[22:25]
	v_mfma_f32_16x16x32_bf16 v[26:29], v[62:65], v[18:21], v[26:29]
	v_mfma_f32_16x16x32_bf16 v[30:33], v[66:69], v[18:21], v[30:33]
	v_mfma_f32_16x16x32_bf16 v[34:37], v[70:73], v[18:21], v[34:37]
	v_mfma_f32_16x16x32_bf16 v[38:41], v[74:77], v[18:21], v[38:41]
	v_mfma_f32_16x16x32_bf16 v[42:45], v[78:81], v[18:21], v[42:45]
	v_mfma_f32_16x16x32_bf16 v[46:49], v[82:85], v[18:21], v[46:49]
	v_mfma_f32_16x16x32_bf16 v[14:17], v[50:53], v[18:21], v[14:17]
	ds_read_b128 v[18:21], v150 offset:3392
	ds_read_b128 v[50:53], v97 offset:7584
	s_waitcnt lgkmcnt(1)
	v_mfma_f32_16x16x32_bf16 v[22:25], v[54:57], v[18:21], v[22:25]
	v_mfma_f32_16x16x32_bf16 v[26:29], v[58:61], v[18:21], v[26:29]
	v_mfma_f32_16x16x32_bf16 v[30:33], v[62:65], v[18:21], v[30:33]
	v_mfma_f32_16x16x32_bf16 v[34:37], v[66:69], v[18:21], v[34:37]
	v_mfma_f32_16x16x32_bf16 v[38:41], v[70:73], v[18:21], v[38:41]
	v_mfma_f32_16x16x32_bf16 v[42:45], v[74:77], v[18:21], v[42:45]
	v_mfma_f32_16x16x32_bf16 v[46:49], v[78:81], v[18:21], v[46:49]
	v_mfma_f32_16x16x32_bf16 v[14:17], v[82:85], v[18:21], v[14:17]
	ds_read_b128 v[18:21], v150 offset:3456
	ds_read_b128 v[82:85], v97 offset:7648
	s_waitcnt lgkmcnt(1)
	v_mfma_f32_16x16x32_bf16 v[22:25], v[50:53], v[18:21], v[22:25]
	v_mfma_f32_16x16x32_bf16 v[26:29], v[54:57], v[18:21], v[26:29]
	v_mfma_f32_16x16x32_bf16 v[30:33], v[58:61], v[18:21], v[30:33]
	v_mfma_f32_16x16x32_bf16 v[34:37], v[62:65], v[18:21], v[34:37]
	v_mfma_f32_16x16x32_bf16 v[38:41], v[66:69], v[18:21], v[38:41]
	v_mfma_f32_16x16x32_bf16 v[42:45], v[70:73], v[18:21], v[42:45]
	v_mfma_f32_16x16x32_bf16 v[46:49], v[74:77], v[18:21], v[46:49]
	v_mfma_f32_16x16x32_bf16 v[14:17], v[78:81], v[18:21], v[14:17]
	ds_read_b128 v[18:21], v150 offset:3520
	ds_read_b128 v[78:81], v97 offset:7712
	s_waitcnt lgkmcnt(1)
	v_mfma_f32_16x16x32_bf16 v[22:25], v[82:85], v[18:21], v[22:25]
	v_mfma_f32_16x16x32_bf16 v[26:29], v[50:53], v[18:21], v[26:29]
	v_mfma_f32_16x16x32_bf16 v[30:33], v[54:57], v[18:21], v[30:33]
	v_mfma_f32_16x16x32_bf16 v[34:37], v[58:61], v[18:21], v[34:37]
	v_mfma_f32_16x16x32_bf16 v[38:41], v[62:65], v[18:21], v[38:41]
	v_mfma_f32_16x16x32_bf16 v[42:45], v[66:69], v[18:21], v[42:45]
	v_mfma_f32_16x16x32_bf16 v[46:49], v[70:73], v[18:21], v[46:49]
	v_mfma_f32_16x16x32_bf16 v[14:17], v[74:77], v[18:21], v[14:17]
	ds_read_b128 v[18:21], v150 offset:3584
	ds_read_b128 v[74:77], v97 offset:7776
	s_waitcnt lgkmcnt(1)
	v_mfma_f32_16x16x32_bf16 v[22:25], v[78:81], v[18:21], v[22:25]
	v_mfma_f32_16x16x32_bf16 v[26:29], v[82:85], v[18:21], v[26:29]
	v_mfma_f32_16x16x32_bf16 v[30:33], v[50:53], v[18:21], v[30:33]
	v_mfma_f32_16x16x32_bf16 v[34:37], v[54:57], v[18:21], v[34:37]
	v_mfma_f32_16x16x32_bf16 v[38:41], v[58:61], v[18:21], v[38:41]
	v_mfma_f32_16x16x32_bf16 v[42:45], v[62:65], v[18:21], v[42:45]
	v_mfma_f32_16x16x32_bf16 v[46:49], v[66:69], v[18:21], v[46:49]
	v_mfma_f32_16x16x32_bf16 v[14:17], v[70:73], v[18:21], v[14:17]
	ds_read_b128 v[18:21], v150 offset:3648
	ds_read_b128 v[70:73], v97 offset:7840
	s_waitcnt lgkmcnt(1)
	v_mfma_f32_16x16x32_bf16 v[22:25], v[74:77], v[18:21], v[22:25]
	v_mfma_f32_16x16x32_bf16 v[26:29], v[78:81], v[18:21], v[26:29]
	v_mfma_f32_16x16x32_bf16 v[30:33], v[82:85], v[18:21], v[30:33]
	v_mfma_f32_16x16x32_bf16 v[34:37], v[50:53], v[18:21], v[34:37]
	v_mfma_f32_16x16x32_bf16 v[38:41], v[54:57], v[18:21], v[38:41]
	v_mfma_f32_16x16x32_bf16 v[42:45], v[58:61], v[18:21], v[42:45]
	v_mfma_f32_16x16x32_bf16 v[46:49], v[62:65], v[18:21], v[46:49]
	v_mfma_f32_16x16x32_bf16 v[18:21], v[66:69], v[18:21], v[14:17]
	ds_read_b128 v[66:69], v150 offset:3712
	s_nop 1
	ds_read_b128 v[14:17], v97 offset:7904
	s_waitcnt lgkmcnt(1)
	v_mfma_f32_16x16x32_bf16 v[22:25], v[70:73], v[66:69], v[22:25]
	v_mfma_f32_16x16x32_bf16 v[26:29], v[74:77], v[66:69], v[26:29]
	v_mfma_f32_16x16x32_bf16 v[30:33], v[78:81], v[66:69], v[30:33]
	v_mfma_f32_16x16x32_bf16 v[34:37], v[82:85], v[66:69], v[34:37]
	v_mfma_f32_16x16x32_bf16 v[38:41], v[50:53], v[66:69], v[38:41]
	v_mfma_f32_16x16x32_bf16 v[42:45], v[54:57], v[66:69], v[42:45]
	v_mfma_f32_16x16x32_bf16 v[46:49], v[58:61], v[66:69], v[46:49]
	v_mfma_f32_16x16x32_bf16 v[62:65], v[62:65], v[66:69], v[18:21]
	ds_read_b128 v[66:69], v150 offset:3776
	s_nop 1
	ds_read_b128 v[18:21], v97 offset:7968
	s_waitcnt lgkmcnt(1)
	v_mfma_f32_16x16x32_bf16 v[58:61], v[58:61], v[66:69], v[62:65]
	s_nop 2
	ds_read_b128 v[62:65], v150 offset:3840
	v_mfma_f32_16x16x32_bf16 v[22:25], v[14:17], v[66:69], v[22:25]
	v_mfma_f32_16x16x32_bf16 v[26:29], v[70:73], v[66:69], v[26:29]
	v_mfma_f32_16x16x32_bf16 v[30:33], v[74:77], v[66:69], v[30:33]
	v_mfma_f32_16x16x32_bf16 v[34:37], v[78:81], v[66:69], v[34:37]
	v_mfma_f32_16x16x32_bf16 v[38:41], v[82:85], v[66:69], v[38:41]
	v_mfma_f32_16x16x32_bf16 v[42:45], v[50:53], v[66:69], v[42:45]
	v_mfma_f32_16x16x32_bf16 v[46:49], v[54:57], v[66:69], v[46:49]
	s_waitcnt lgkmcnt(0)
	v_mfma_f32_16x16x32_bf16 v[66:69], v[18:21], v[62:65], v[22:25]
	s_nop 2
	ds_read_b128 v[22:25], v97 offset:8032
	v_mfma_f32_16x16x32_bf16 v[54:57], v[54:57], v[62:65], v[58:61]
	s_nop 2
	ds_read_b128 v[58:61], v150 offset:3904
	v_mfma_f32_16x16x32_bf16 v[26:29], v[14:17], v[62:65], v[26:29]
	v_mfma_f32_16x16x32_bf16 v[30:33], v[70:73], v[62:65], v[30:33]
	v_mfma_f32_16x16x32_bf16 v[34:37], v[74:77], v[62:65], v[34:37]
	v_mfma_f32_16x16x32_bf16 v[38:41], v[78:81], v[62:65], v[38:41]
	v_mfma_f32_16x16x32_bf16 v[42:45], v[82:85], v[62:65], v[42:45]
	v_mfma_f32_16x16x32_bf16 v[46:49], v[50:53], v[62:65], v[46:49]
	s_waitcnt lgkmcnt(0)
	v_mfma_f32_16x16x32_bf16 v[62:65], v[22:25], v[58:61], v[66:69]
	v_mfma_f32_16x16x32_bf16 v[66:69], v[18:21], v[58:61], v[26:29]
	s_nop 2
	ds_read_b128 v[26:29], v97 offset:8096
	v_mfma_f32_16x16x32_bf16 v[50:53], v[50:53], v[58:61], v[54:57]
	s_nop 2
	ds_read_b128 v[54:57], v150 offset:3968
	v_mfma_f32_16x16x32_bf16 v[30:33], v[14:17], v[58:61], v[30:33]
	v_mfma_f32_16x16x32_bf16 v[34:37], v[70:73], v[58:61], v[34:37]
	v_mfma_f32_16x16x32_bf16 v[38:41], v[74:77], v[58:61], v[38:41]
	v_mfma_f32_16x16x32_bf16 v[42:45], v[78:81], v[58:61], v[42:45]
	v_mfma_f32_16x16x32_bf16 v[46:49], v[82:85], v[58:61], v[46:49]
	s_waitcnt lgkmcnt(0)
	v_mfma_f32_16x16x32_bf16 v[58:61], v[26:29], v[54:57], v[62:65]
	v_mfma_f32_16x16x32_bf16 v[62:65], v[22:25], v[54:57], v[66:69]
	v_mfma_f32_16x16x32_bf16 v[66:69], v[18:21], v[54:57], v[30:33]
	v_mfma_f32_16x16x32_bf16 v[34:37], v[14:17], v[54:57], v[34:37]
	s_nop 1
	ds_read_b128 v[30:33], v97 offset:8160
	v_mfma_f32_16x16x32_bf16 v[38:41], v[70:73], v[54:57], v[38:41]
	v_mfma_f32_16x16x32_bf16 v[42:45], v[74:77], v[54:57], v[42:45]
	v_mfma_f32_16x16x32_bf16 v[46:49], v[78:81], v[54:57], v[46:49]
	v_mfma_f32_16x16x32_bf16 v[50:53], v[82:85], v[54:57], v[50:53]
	ds_read_b128 v[54:57], v150 offset:4032
	s_waitcnt lgkmcnt(0)
	v_mfma_f32_16x16x32_bf16 v[82:85], v[70:73], v[54:57], v[42:45]
	s_nop 2
	ds_read_b128 v[42:45], v97 offset:8224
	v_mfma_f32_16x16x32_bf16 v[50:53], v[78:81], v[54:57], v[50:53]
	ds_read_b128 v[78:81], v150 offset:4096
	v_mfma_f32_16x16x32_bf16 v[58:61], v[30:33], v[54:57], v[58:61]
	v_mfma_f32_16x16x32_bf16 v[62:65], v[26:29], v[54:57], v[62:65]
	v_mfma_f32_16x16x32_bf16 v[66:69], v[22:25], v[54:57], v[66:69]
	v_mfma_f32_16x16x32_bf16 v[34:37], v[18:21], v[54:57], v[34:37]
	v_mfma_f32_16x16x32_bf16 v[38:41], v[14:17], v[54:57], v[38:41]
	v_mfma_f32_16x16x32_bf16 v[46:49], v[74:77], v[54:57], v[46:49]
	ds_read_b128 v[54:57], v97 offset:8288
	s_waitcnt lgkmcnt(1)
	v_mfma_f32_16x16x32_bf16 v[58:61], v[42:45], v[78:81], v[58:61]
	v_mfma_f32_16x16x32_bf16 v[140:143], v[30:33], v[78:81], v[62:65]
	v_mfma_f32_16x16x32_bf16 v[144:147], v[26:29], v[78:81], v[66:69]
	v_mfma_f32_16x16x32_bf16 v[34:37], v[22:25], v[78:81], v[34:37]
	v_mfma_f32_16x16x32_bf16 v[38:41], v[18:21], v[78:81], v[38:41]
	v_mfma_f32_16x16x32_bf16 v[82:85], v[14:17], v[78:81], v[82:85]
	v_mfma_f32_16x16x32_bf16 v[190:193], v[70:73], v[78:81], v[46:49]
	v_mfma_f32_16x16x32_bf16 v[74:77], v[74:77], v[78:81], v[50:53]
	ds_read_b128 v[78:81], v150 offset:4160
	s_waitcnt lgkmcnt(0)
	v_mfma_f32_16x16x32_bf16 v[70:73], v[70:73], v[78:81], v[74:77]
	s_nop 4
	ds_read_b128 v[74:77], v150 offset:4224
	v_mfma_f32_16x16x32_bf16 v[50:53], v[26:29], v[78:81], v[34:37]
	v_mfma_f32_16x16x32_bf16 v[46:49], v[22:25], v[78:81], v[38:41]
	v_mfma_f32_16x16x32_bf16 v[38:41], v[18:21], v[78:81], v[82:85]
	s_nop 2
	ds_read_b128 v[82:85], v97 offset:8352
	v_mfma_f32_16x16x32_bf16 v[62:65], v[54:57], v[78:81], v[58:61]
	v_mfma_f32_16x16x32_bf16 v[58:61], v[30:33], v[78:81], v[144:147]
	s_waitcnt lgkmcnt(1)
	v_mfma_f32_16x16x32_bf16 v[30:33], v[30:33], v[74:77], v[50:53]
	s_nop 0
	v_mov_b32_e32 v147, 0
	s_nop 0
	v_lshl_add_u64 v[50:51], s[42:43], 0, v[134:135]
	v_mfma_f32_16x16x32_bf16 v[26:29], v[26:29], v[74:77], v[46:49]
	v_mov_b32_e32 v135, 0
	s_nop 1
	v_lshl_add_u64 v[46:47], v[98:99], 1, v[50:51]
	v_add_co_u32_e32 v48, vcc, 0x4000, v46
	v_mfma_f32_16x16x32_bf16 v[66:69], v[42:45], v[78:81], v[140:143]
	s_nop 0
	v_addc_co_u32_e32 v49, vcc, 0, v47, vcc
	global_load_dwordx2 v[144:145], v[48:49], off
	v_mfma_f32_16x16x32_bf16 v[34:37], v[14:17], v[78:81], v[190:193]
	s_waitcnt lgkmcnt(0)
	v_mfma_f32_16x16x32_bf16 v[62:65], v[82:85], v[74:77], v[62:65]
	v_mfma_f32_16x16x32_bf16 v[54:57], v[54:57], v[74:77], v[66:69]
	v_mfma_f32_16x16x32_bf16 v[42:45], v[42:45], v[74:77], v[58:61]
	v_mfma_f32_16x16x32_bf16 v[22:25], v[22:25], v[74:77], v[38:41]
	v_mfma_f32_16x16x32_bf16 v[18:21], v[18:21], v[74:77], v[34:37]
	v_mfma_f32_16x16x32_bf16 v[14:17], v[14:17], v[74:77], v[70:73]
	s_nop 1
	v_lshl_add_u64 v[34:35], v[46:47], 0, s[16:17]
	s_mov_b64 s[4:5], exec
	v_readlane_b32 s6, v255, 37
	v_readlane_b32 s7, v255, 38
	s_and_b64 s[6:7], s[4:5], s[6:7]
	s_mov_b64 exec, s[6:7]
	s_cbranch_execz .LBB0_868
	global_load_short_d16_hi v147, v[34:35], off offset:-2
